# hoist row-rstd loads also in in-proj (EpiIn) and gate (EpiMerge2) GEMM epilogues
# speedup vs baseline: 1.0924x; 1.0008x over previous
; __device__ __forceinline__ float row_rstd(const float* ssp, int row, int fq) {
;     const f32x4 t = *((const f32x4*)(ssp + (size_t)row * 16) + fq); float s = (t[0] + t[1]) + (t[2] + t[3]); s += __shfl_xor(s, 16); s += __shfl_xor(s, 32); return rsqrtf(s * (1.0f / DM) + EPS); }
;     __device__ __forceinline__ void operator()(const f32x4 (&acc)[2][2][4][2], const Unit& u, int wr, int wc, int fr, int fq) const {
;         const int T = u.pn; const int row0 = u.pm * BM + wr * 64 + fr;
;         unsigned char* const chb = ws + WS_SLAB + (size_t)(u.pm >> 4) * SLAB; const int lrow0 = row0 & (SEQ - 1);
;         bf16_t* const Q = (bf16_t*)(chb + SL_Q); bf16_t* const K = (bf16_t*)(chb + SL_K); bf16_t* const Vt = (bf16_t*)(chb + SL_V); bf16_t* const GLU = (bf16_t*)(chb + SL_GLU);
;         bf16_t* const P = (bf16_t*)(chb + SL_P); bf16_t* const BG = (bf16_t*)(ws + WS_HCBG) + 512;
;         float rx[2][4];
; #pragma unroll
;         for (int ai = 0; ai < 2; ++ai)
; #pragma unroll
;             for (int m = 0; m < 4; ++m) rx[ai][m] = row_rstd(ssp, row0 + ai * HALF + m * 16, fq);
;         if (T < 4) {
.LBB0_203:
	v_and_b32_e32 v129, 64, v229
	v_xor_b32_e32 v128, 16, v229
	v_add_u32_e32 v129, 64, v129
	v_cmp_lt_i32_e32 vcc, v128, v129
	v_lshl_add_u32 v132, s42, 8, v153
	v_ashrrev_i32_e32 v133, 31, v132
	v_cndmask_b32_e32 v128, v229, v128, vcc
	v_lshlrev_b32_e32 v169, 2, v128
	v_xor_b32_e32 v128, 32, v229
	v_cmp_lt_i32_e32 vcc, v128, v129
	s_mov_b32 s4, 0x358637bd
	v_mov_b64_e32 v[140:141], s[4:5]
	v_cndmask_b32_e32 v128, v229, v128, vcc
	v_lshlrev_b32_e32 v167, 2, v128
	v_lshlrev_b64 v[128:129], 6, v[132:133]
	v_lshl_add_u64 v[128:129], v[154:155], 0, v[128:129]
	global_load_dwordx4 v[186:189], v[128:129], off
	global_load_dwordx4 v[194:197], v[128:129], off offset:1024
	global_load_dwordx4 v[198:201], v[128:129], off offset:2048
	global_load_dwordx4 v[202:205], v[128:129], off offset:3072
	v_add_co_u32_e32 v184, vcc, 0x2000, v128
	s_nop 1
	v_addc_co_u32_e32 v185, vcc, 0, v129, vcc
	global_load_dwordx4 v[206:209], v[184:185], off
	global_load_dwordx4 v[210:213], v[184:185], off offset:1024
	global_load_dwordx4 v[214:217], v[184:185], off offset:2048
	global_load_dwordx4 v[218:221], v[184:185], off offset:3072
	s_ashr_i32 s19, s42, 4
	v_add_u32_e32 v178, 0x90, v132
	v_ashrrev_i32_e32 v179, 31, v178
	v_add_u32_e32 v180, 0xa0, v132
	v_ashrrev_i32_e32 v181, 31, v180
	v_add_u32_e32 v182, 0xb0, v132
	v_ashrrev_i32_e32 v183, 31, v182
	s_mul_hi_i32 s18, s19, 0x1c00000
	s_mul_i32 s19, s19, 0x1c00000
	s_add_u32 s49, s72, s19
	s_addc_u32 s51, s73, s18
	v_and_b32_e32 v171, 0xfcf, v132
	s_cmp_gt_i32 s75, 3
	s_waitcnt vmcnt(7)
	v_mov_b32_e32 v134, v187
	v_mov_b32_e32 v135, v188
	v_mov_b32_e32 v187, v189
	v_pk_add_f32 v[136:137], v[134:135], v[186:187]
	v_or_b32_e32 v134, 16, v132
	v_ashrrev_i32_e32 v135, 31, v134
	s_waitcnt vmcnt(6)
	v_mov_b32_e32 v138, v195
	v_mov_b32_e32 v139, v196
	v_mov_b32_e32 v195, v197
	v_pk_add_f32 v[128:129], v[138:139], v[194:195]
	v_mov_b32_e32 v131, v136
	v_mov_b32_e32 v130, v128
	v_mov_b32_e32 v136, v129
	v_pk_add_f32 v[128:129], v[130:131], v[136:137]
	ds_bpermute_b32 v131, v169, v129
	ds_bpermute_b32 v130, v169, v128
	v_or_b32_e32 v138, 32, v132
	v_ashrrev_i32_e32 v139, 31, v138
	s_waitcnt lgkmcnt(0)
	v_pk_add_f32 v[128:129], v[128:129], v[130:131]
	ds_bpermute_b32 v131, v167, v129
	ds_bpermute_b32 v130, v167, v128
	s_waitcnt lgkmcnt(0)
	v_pk_add_f32 v[128:129], v[128:129], v[130:131]
	s_nop 0
	v_pk_fma_f32 v[128:129], v[128:129], s[38:39], v[140:141] op_sel_hi:[1,0,0]
	s_nop 0
	v_mul_f32_e32 v130, 0x4b800000, v129
	v_cmp_gt_f32_e64 s[42:43], s99, v129
	v_cmp_gt_f32_e32 vcc, s99, v128
	s_nop 0
	v_cndmask_b32_e64 v129, v129, v130, s[42:43]
	v_rsq_f32_e32 v129, v129
	s_nop 0
	v_mul_f32_e32 v130, 0x45800000, v129
	v_cndmask_b32_e64 v170, v129, v130, s[42:43]
	v_mul_f32_e32 v129, 0x4b800000, v128
	v_cndmask_b32_e32 v128, v128, v129, vcc
	v_rsq_f32_e32 v128, v128
	s_nop 0
	v_mul_f32_e32 v129, 0x45800000, v128
	v_cndmask_b32_e32 v166, v128, v129, vcc
	s_waitcnt vmcnt(5)
	v_mov_b32_e32 v136, v199
	v_mov_b32_e32 v137, v200
	v_mov_b32_e32 v199, v201
	v_pk_add_f32 v[142:143], v[136:137], v[198:199]
	v_or_b32_e32 v136, 48, v132
	v_ashrrev_i32_e32 v137, 31, v136
	s_waitcnt vmcnt(4)
	v_mov_b32_e32 v172, v203
	v_mov_b32_e32 v173, v204
	v_mov_b32_e32 v203, v205
	v_pk_add_f32 v[128:129], v[172:173], v[202:203]
	v_mov_b32_e32 v131, v142
	v_mov_b32_e32 v130, v128
	v_mov_b32_e32 v142, v129
	v_pk_add_f32 v[128:129], v[130:131], v[142:143]
	ds_bpermute_b32 v131, v169, v129
	ds_bpermute_b32 v130, v169, v128
	v_add_u32_e32 v142, 0x80, v132
	v_ashrrev_i32_e32 v143, 31, v142
	s_waitcnt lgkmcnt(0)
	v_pk_add_f32 v[128:129], v[128:129], v[130:131]
	ds_bpermute_b32 v131, v167, v129
	ds_bpermute_b32 v130, v167, v128
	s_waitcnt lgkmcnt(0)
	v_pk_add_f32 v[128:129], v[128:129], v[130:131]
	s_nop 0
	v_pk_fma_f32 v[128:129], v[128:129], s[38:39], v[140:141] op_sel_hi:[1,0,0]
	s_nop 0
	v_mul_f32_e32 v130, 0x4b800000, v129
	v_cmp_gt_f32_e64 s[42:43], s99, v129
	v_cmp_gt_f32_e32 vcc, s99, v128
	s_nop 0
	v_cndmask_b32_e64 v129, v129, v130, s[42:43]
	v_rsq_f32_e32 v129, v129
	s_nop 0
	v_mul_f32_e32 v130, 0x45800000, v129
	v_cndmask_b32_e64 v172, v129, v130, s[42:43]
	v_mul_f32_e32 v129, 0x4b800000, v128
	v_cndmask_b32_e32 v128, v128, v129, vcc
	v_rsq_f32_e32 v128, v128
	s_nop 0
	v_mul_f32_e32 v129, 0x45800000, v128
	v_cndmask_b32_e32 v164, v128, v129, vcc
	s_waitcnt vmcnt(3)
	v_mov_b32_e32 v174, v207
	v_mov_b32_e32 v175, v208
	v_mov_b32_e32 v207, v209
	v_pk_add_f32 v[174:175], v[174:175], v[206:207]
	s_waitcnt vmcnt(2)
	v_mov_b32_e32 v176, v211
	v_mov_b32_e32 v177, v212
	v_mov_b32_e32 v211, v213
	v_pk_add_f32 v[128:129], v[176:177], v[210:211]
	v_mov_b32_e32 v131, v174
	v_mov_b32_e32 v130, v128
	v_mov_b32_e32 v174, v129
	v_pk_add_f32 v[128:129], v[130:131], v[174:175]
	ds_bpermute_b32 v131, v169, v129
	ds_bpermute_b32 v130, v169, v128
	s_waitcnt lgkmcnt(0)
	v_pk_add_f32 v[128:129], v[128:129], v[130:131]
	ds_bpermute_b32 v131, v167, v129
	ds_bpermute_b32 v130, v167, v128
	s_waitcnt lgkmcnt(0)
	v_pk_add_f32 v[128:129], v[128:129], v[130:131]
	s_nop 0
	v_pk_fma_f32 v[128:129], v[128:129], s[38:39], v[140:141] op_sel_hi:[1,0,0]
	s_nop 0
	v_mul_f32_e32 v130, 0x4b800000, v129
	v_cmp_gt_f32_e64 s[42:43], s99, v129
	v_cmp_gt_f32_e32 vcc, s99, v128
	s_nop 0
	v_cndmask_b32_e64 v129, v129, v130, s[42:43]
	v_rsq_f32_e32 v129, v129
	s_nop 0
	v_mul_f32_e32 v130, 0x45800000, v129
	v_cndmask_b32_e64 v168, v129, v130, s[42:43]
	v_mul_f32_e32 v129, 0x4b800000, v128
	v_cndmask_b32_e32 v128, v128, v129, vcc
	v_rsq_f32_e32 v128, v128
	s_nop 0
	v_mul_f32_e32 v129, 0x45800000, v128
	v_cndmask_b32_e32 v162, v128, v129, vcc
	s_waitcnt vmcnt(1)
	v_mov_b32_e32 v174, v215
	v_mov_b32_e32 v175, v216
	v_mov_b32_e32 v215, v217
	v_pk_add_f32 v[174:175], v[174:175], v[214:215]
	s_waitcnt vmcnt(0)
	v_mov_b32_e32 v176, v219
	v_mov_b32_e32 v177, v220
	v_mov_b32_e32 v219, v221
	v_pk_add_f32 v[128:129], v[176:177], v[218:219]
	v_mov_b32_e32 v131, v174
	v_mov_b32_e32 v130, v128
	v_mov_b32_e32 v174, v129
	v_pk_add_f32 v[128:129], v[130:131], v[174:175]
	ds_bpermute_b32 v131, v169, v129
	ds_bpermute_b32 v130, v169, v128
	s_waitcnt lgkmcnt(0)
	v_pk_add_f32 v[128:129], v[128:129], v[130:131]
	ds_bpermute_b32 v131, v167, v129
	ds_bpermute_b32 v130, v167, v128
	s_waitcnt lgkmcnt(0)
	v_pk_add_f32 v[128:129], v[128:129], v[130:131]
	s_nop 0
	v_pk_fma_f32 v[128:129], v[128:129], s[38:39], v[140:141] op_sel_hi:[1,0,0]
	s_nop 0
	v_mul_f32_e32 v130, 0x4b800000, v129
	v_cmp_gt_f32_e64 s[42:43], s99, v129
	v_cmp_gt_f32_e32 vcc, s99, v128
	s_nop 0
	v_cndmask_b32_e64 v129, v129, v130, s[42:43]
	v_rsq_f32_e32 v129, v129
	s_nop 0
	v_mul_f32_e32 v130, 0x45800000, v129
	v_cndmask_b32_e64 v176, v129, v130, s[42:43]
	v_mul_f32_e32 v129, 0x4b800000, v128
	v_cndmask_b32_e32 v128, v128, v129, vcc
	v_rsq_f32_e32 v128, v128
	s_mov_b64 s[42:43], -1
	v_mul_f32_e32 v129, 0x45800000, v128
	v_cndmask_b32_e32 v174, v128, v129, vcc
	s_cbranch_scc1 .LBB0_206
	s_andn2_b64 vcc, exec, s[42:43]
	s_cbranch_vccz .LBB0_215

; __device__ __forceinline__ float row_rstd(const float* ssp, int row, int fq) {
;     const f32x4 t = *((const f32x4*)(ssp + (size_t)row * 16) + fq); float s = (t[0] + t[1]) + (t[2] + t[3]); s += __shfl_xor(s, 16); s += __shfl_xor(s, 32); return rsqrtf(s * (1.0f / DM) + EPS); }
;     __device__ __forceinline__ void operator()(const f32x4 (&acc)[2][2][4][2], const Unit& u, int wr, int wc, int fr, int fq) const {
;     ...
;         const int row0 = u.pm * BM + wr * 64 + fr, col0 = u.pn * BM + 32 * wc + 8 * fq;
;         if (part == 1) {
;             float rx[2][4];
; #pragma unroll
;             for (int ai = 0; ai < 2; ++ai)
; #pragma unroll
;                 for (int m = 0; m < 4; ++m) rx[ai][m] = row_rstd(ssp, row0 + ai * HALF + m * 16, fq);
.LBB0_558:
	s_and_b64 vcc, exec, s[18:19]
	s_cbranch_vccz .LBB0_560
	v_and_b32_e32 v129, 64, v229
	v_xor_b32_e32 v128, 16, v229
	v_add_u32_e32 v129, 64, v129
	v_cmp_lt_i32_e32 vcc, v128, v129
	v_ashrrev_i32_e32 v211, 31, v210
	s_mov_b32 s10, 0x358637bd
	v_cndmask_b32_e32 v128, v229, v128, vcc
	v_lshlrev_b32_e32 v140, 2, v128
	v_xor_b32_e32 v128, 32, v229
	v_cmp_lt_i32_e32 vcc, v128, v129
	v_mov_b32_e32 v209, v193
	s_nop 0
	v_cndmask_b32_e32 v128, v229, v128, vcc
	v_lshlrev_b32_e32 v141, 2, v128
	v_lshlrev_b64 v[128:129], 6, v[210:211]
	v_lshl_add_u64 v[130:131], v[202:203], 0, v[128:129]
	global_load_dwordx4 v[156:159], v[130:131], off
	global_load_dwordx4 v[160:163], v[130:131], off offset:1024
	global_load_dwordx4 v[164:167], v[130:131], off offset:2048
	global_load_dwordx4 v[168:171], v[130:131], off offset:3072
	v_add_co_u32_e32 v188, vcc, 0x2000, v130
	s_nop 1
	v_addc_co_u32_e32 v189, vcc, 0, v131, vcc
	global_load_dwordx4 v[172:175], v[188:189], off
	global_load_dwordx4 v[176:179], v[188:189], off offset:1024
	global_load_dwordx4 v[180:183], v[188:189], off offset:2048
	global_load_dwordx4 v[184:187], v[188:189], off offset:3072
	s_waitcnt vmcnt(7)
	v_mov_b32_e32 v128, v157
	v_mov_b32_e32 v129, v158
	v_mov_b32_e32 v157, v159
	v_pk_add_f32 v[128:129], v[128:129], v[156:157]
	s_waitcnt vmcnt(6)
	v_mov_b32_e32 v136, v161
	v_mov_b32_e32 v137, v162
	v_mov_b32_e32 v161, v163
	v_pk_add_f32 v[132:133], v[136:137], v[160:161]
	v_mov_b32_e32 v135, v128
	v_mov_b32_e32 v134, v132
	v_mov_b32_e32 v128, v133
	v_pk_add_f32 v[128:129], v[134:135], v[128:129]
	ds_bpermute_b32 v133, v140, v129
	ds_bpermute_b32 v132, v140, v128
	s_waitcnt lgkmcnt(0)
	v_pk_add_f32 v[128:129], v[128:129], v[132:133]
	ds_bpermute_b32 v133, v141, v129
	ds_bpermute_b32 v132, v141, v128
	s_waitcnt lgkmcnt(0)
	v_pk_add_f32 v[132:133], v[128:129], v[132:133]
	v_mov_b64_e32 v[128:129], s[10:11]
	v_pk_fma_f32 v[132:133], v[132:133], s[38:39], v[128:129] op_sel_hi:[1,0,0]
	s_and_b32 s10, 0xffff, s52
	v_mul_f32_e32 v134, 0x4b800000, v133
	v_cmp_gt_f32_e64 s[42:43], s99, v133
	v_cmp_gt_f32_e32 vcc, s99, v132
	s_lshl_b32 s10, s10, 12
	v_cndmask_b32_e64 v133, v133, v134, s[42:43]
	v_rsq_f32_e32 v133, v133
	s_add_u32 s10, s63, s10
	s_addc_u32 s11, s64, 0
	v_mul_f32_e32 v134, 0x45800000, v133
	v_cndmask_b32_e64 v147, v133, v134, s[42:43]
	v_mul_f32_e32 v133, 0x4b800000, v132
	v_cndmask_b32_e32 v132, v132, v133, vcc
	v_rsq_f32_e32 v132, v132
	s_nop 0
	v_mul_f32_e32 v133, 0x45800000, v132
	v_cndmask_b32_e32 v145, v132, v133, vcc
	s_waitcnt vmcnt(5)
	v_mov_b32_e32 v136, v165
	v_mov_b32_e32 v137, v166
	v_mov_b32_e32 v165, v167
	v_pk_add_f32 v[136:137], v[136:137], v[164:165]
	s_waitcnt vmcnt(4)
	v_mov_b32_e32 v138, v169
	v_mov_b32_e32 v139, v170
	v_mov_b32_e32 v169, v171
	v_pk_add_f32 v[132:133], v[138:139], v[168:169]
	v_mov_b32_e32 v135, v136
	v_mov_b32_e32 v134, v132
	v_mov_b32_e32 v136, v133
	v_pk_add_f32 v[132:133], v[134:135], v[136:137]
	ds_bpermute_b32 v135, v140, v133
	ds_bpermute_b32 v134, v140, v132
	s_waitcnt lgkmcnt(0)
	v_pk_add_f32 v[132:133], v[132:133], v[134:135]
	ds_bpermute_b32 v135, v141, v133
	ds_bpermute_b32 v134, v141, v132
	s_waitcnt lgkmcnt(0)
	v_pk_add_f32 v[132:133], v[132:133], v[134:135]
	s_nop 0
	v_pk_fma_f32 v[132:133], v[132:133], s[38:39], v[128:129] op_sel_hi:[1,0,0]
	s_nop 0
	v_mul_f32_e32 v134, 0x4b800000, v133
	v_cmp_gt_f32_e64 s[42:43], s99, v133
	v_cmp_gt_f32_e32 vcc, s99, v132
	s_nop 0
	v_cndmask_b32_e64 v133, v133, v134, s[42:43]
	v_rsq_f32_e32 v133, v133
	s_nop 0
	v_mul_f32_e32 v134, 0x45800000, v133
	v_cndmask_b32_e64 v146, v133, v134, s[42:43]
	v_mul_f32_e32 v133, 0x4b800000, v132
	v_cndmask_b32_e32 v132, v132, v133, vcc
	v_rsq_f32_e32 v132, v132
	s_nop 0
	v_mul_f32_e32 v133, 0x45800000, v132
	v_cndmask_b32_e32 v143, v132, v133, vcc
	s_waitcnt vmcnt(3)
	v_mov_b32_e32 v136, v173
	v_mov_b32_e32 v137, v174
	v_mov_b32_e32 v173, v175
	v_pk_add_f32 v[136:137], v[136:137], v[172:173]
	s_waitcnt vmcnt(2)
	v_mov_b32_e32 v138, v177
	v_mov_b32_e32 v139, v178
	v_mov_b32_e32 v177, v179
	v_pk_add_f32 v[130:131], v[138:139], v[176:177]
	v_mov_b32_e32 v133, v136
	v_mov_b32_e32 v132, v130
	v_mov_b32_e32 v136, v131
	v_pk_add_f32 v[130:131], v[132:133], v[136:137]
	ds_bpermute_b32 v133, v140, v131
	ds_bpermute_b32 v132, v140, v130
	v_lshl_add_u64 v[138:139], v[208:209], 2, s[10:11]
	s_mov_b32 s10, 0x8000
	s_waitcnt lgkmcnt(0)
	v_pk_add_f32 v[130:131], v[130:131], v[132:133]
	ds_bpermute_b32 v133, v141, v131
	ds_bpermute_b32 v132, v141, v130
	s_waitcnt lgkmcnt(0)
	v_pk_add_f32 v[130:131], v[130:131], v[132:133]
	s_nop 0
	v_pk_fma_f32 v[130:131], v[130:131], s[38:39], v[128:129] op_sel_hi:[1,0,0]
	s_nop 0
	v_mul_f32_e32 v132, 0x4b800000, v131
	v_cmp_gt_f32_e64 s[42:43], s99, v131
	v_cmp_gt_f32_e32 vcc, s99, v130
	s_nop 0
	v_cndmask_b32_e64 v131, v131, v132, s[42:43]
	v_rsq_f32_e32 v131, v131
	s_nop 0
	v_mul_f32_e32 v132, 0x45800000, v131
	v_cndmask_b32_e64 v144, v131, v132, s[42:43]
	v_mul_f32_e32 v131, 0x4b800000, v130
	v_cndmask_b32_e32 v130, v130, v131, vcc
	v_rsq_f32_e32 v130, v130
	s_nop 0
	v_mul_f32_e32 v131, 0x45800000, v130
	v_cndmask_b32_e32 v142, v130, v131, vcc
	s_waitcnt vmcnt(1)
	v_mov_b32_e32 v136, v181
	v_mov_b32_e32 v137, v182
	v_mov_b32_e32 v181, v183
	v_pk_add_f32 v[136:137], v[136:137], v[180:181]
	s_waitcnt vmcnt(0)
	v_mov_b32_e32 v134, v185
	v_mov_b32_e32 v135, v186
	v_mov_b32_e32 v185, v187
	v_pk_add_f32 v[130:131], v[134:135], v[184:185]
	v_mov_b32_e32 v133, v136
	v_mov_b32_e32 v132, v130
	v_mov_b32_e32 v136, v131
	v_pk_add_f32 v[130:131], v[132:133], v[136:137]
	ds_bpermute_b32 v133, v140, v131
	ds_bpermute_b32 v132, v140, v130
	v_lshl_add_u64 v[136:137], s[30:31], 0, v[192:193]
	s_waitcnt lgkmcnt(0)
; __device__ __forceinline__ u32x4 pack8(const f32x4& a, const f32x4& b) { u32x4 w; w.x = pk2(a[0], a[1]); w.y = pk2(a[2], a[3]); w.z = pk2(b[0], b[1]); w.w = pk2(b[2], b[3]); return w; }
; __device__ __forceinline__ float sigm(float x) { return __builtin_amdgcn_rcpf(1.0f + __builtin_amdgcn_exp2f(x * -1.4426950408889634f)); }
;     __device__ __forceinline__ void operator()(const f32x4 (&acc)[2][2][4][2], const Unit& u, int wr, int wc, int fr, int fq) const {
;     ...
;                 for (int m = 0; m < 4; ++m) rx[ai][m] = row_rstd(ssp, row0 + ai * HALF + m * 16, fq);
; #pragma unroll
;             for (int bj = 0; bj < 2; ++bj) {
;                 const f32x4 bv0 = *(const f32x4*)(gb + br * 1024 + col0 + 128 * bj), bv1 = *(const f32x4*)(gb + br * 1024 + col0 + 128 * bj + 4);
; #pragma unroll
;                 for (int ai = 0; ai < 2; ++ai)
; #pragma unroll
;                     for (int m = 0; m < 4; ++m) {
;                         const f32x4 a0 = acc[ai][bj][m][0] * rx[ai][m] + bv0, a1 = acc[ai][bj][m][1] * rx[ai][m] + bv1; f32x4 o0, o1;
; #pragma unroll
;                         for (int e = 0; e < 4; ++e) { o0[e] = sigm(a0[e]); o1[e] = sigm(a1[e]); }
;                         *(u32x4*)(tmpb + ((ai * 4 + m) * 2 + bj) * 8192 + voff) = pack8(o0, o1); }
;                 asm volatile("" ::: "memory"); }
	v_pk_add_f32 v[130:131], v[130:131], v[132:133]
	ds_bpermute_b32 v133, v141, v131
	ds_bpermute_b32 v132, v141, v130
	s_waitcnt lgkmcnt(0)
	v_pk_add_f32 v[130:131], v[130:131], v[132:133]
	s_nop 0
	v_pk_fma_f32 v[128:129], v[130:131], s[38:39], v[128:129] op_sel_hi:[1,0,0]
	s_nop 0
	v_mul_f32_e32 v130, 0x4b800000, v129
	v_cmp_gt_f32_e64 s[42:43], s99, v129
	v_cmp_gt_f32_e32 vcc, s99, v128
	s_nop 0
	v_cndmask_b32_e64 v129, v129, v130, s[42:43]
	v_rsq_f32_e32 v129, v129
	s_nop 0
	v_mul_f32_e32 v130, 0x45800000, v129
	v_cndmask_b32_e64 v141, v129, v130, s[42:43]
	v_mul_f32_e32 v129, 0x4b800000, v128
	v_cndmask_b32_e32 v128, v128, v129, vcc
	v_rsq_f32_e32 v128, v128
	s_nop 0
	v_mul_f32_e32 v129, 0x45800000, v128
	v_cndmask_b32_e32 v140, v128, v129, vcc
	global_load_dwordx4 v[128:131], v[138:139], off offset:16
	global_load_dwordx4 v[132:135], v[138:139], off
	s_waitcnt vmcnt(1)
	v_fma_f32 v149, v120, v147, v128
	v_mul_f32_e32 v149, 0xbfb8aa3b, v149
	v_exp_f32_e32 v149, v149
	s_waitcnt vmcnt(0)
	v_fma_f32 v148, v124, v147, v132
	v_fma_f32 v151, v121, v147, v129
	v_fma_f32 v152, v126, v147, v134
	v_add_f32_e32 v149, 1.0, v149
	v_rcp_f32_e32 v150, v149
	v_fma_f32 v149, v125, v147, v133
	v_fma_f32 v153, v122, v147, v130
	v_fma_f32 v154, v127, v147, v135
	v_fma_f32 v155, v123, v147, v131
	v_mul_f32_e32 v148, 0xbfb8aa3b, v148
	v_mul_f32_e32 v149, 0xbfb8aa3b, v149
	v_mul_f32_e32 v151, 0xbfb8aa3b, v151
	v_mul_f32_e32 v152, 0xbfb8aa3b, v152
	v_mul_f32_e32 v153, 0xbfb8aa3b, v153
	v_mul_f32_e32 v154, 0xbfb8aa3b, v154
	v_mul_f32_e32 v155, 0xbfb8aa3b, v155
	v_exp_f32_e32 v148, v148
	v_exp_f32_e32 v149, v149
	v_exp_f32_e32 v151, v151
	v_exp_f32_e32 v152, v152
	v_exp_f32_e32 v153, v153
	v_exp_f32_e32 v154, v154
	v_exp_f32_e32 v155, v155
	v_add_f32_e32 v148, 1.0, v148
	v_add_f32_e32 v149, 1.0, v149
	v_add_f32_e32 v151, 1.0, v151
	v_add_f32_e32 v152, 1.0, v152
	v_add_f32_e32 v153, 1.0, v153
	v_add_f32_e32 v154, 1.0, v154
	v_add_f32_e32 v155, 1.0, v155
	v_rcp_f32_e32 v148, v148
	v_rcp_f32_e32 v149, v149
	v_rcp_f32_e32 v151, v151
	v_rcp_f32_e32 v152, v152
	v_rcp_f32_e32 v153, v153
	v_rcp_f32_e32 v154, v154
	v_rcp_f32_e32 v155, v155
	v_cvt_pk_bf16_f32 v148, v148, v149
	v_cvt_pk_bf16_f32 v150, v150, v151
	v_cvt_pk_bf16_f32 v149, v152, v154
	v_cvt_pk_bf16_f32 v151, v153, v155
	global_store_dwordx4 v192, v[148:151], s[30:31]
	v_fma_f32 v152, v118, v145, v134
	v_fma_f32 v154, v119, v145, v135
	v_fma_f32 v149, v112, v145, v128
	v_mul_f32_e32 v149, 0xbfb8aa3b, v149
	v_exp_f32_e32 v149, v149
	v_fma_f32 v148, v116, v145, v132
	v_mul_f32_e32 v148, 0xbfb8aa3b, v148
	v_fma_f32 v151, v113, v145, v129
	v_add_f32_e32 v149, 1.0, v149
	v_rcp_f32_e32 v150, v149
	v_fma_f32 v149, v117, v145, v133
	v_mul_f32_e32 v149, 0xbfb8aa3b, v149
	v_mul_f32_e32 v152, 0xbfb8aa3b, v152
	v_fma_f32 v153, v114, v145, v130
	v_mul_f32_e32 v154, 0xbfb8aa3b, v154
	v_fma_f32 v155, v115, v145, v131
	v_exp_f32_e32 v148, v148
	v_exp_f32_e32 v149, v149
	v_mul_f32_e32 v151, 0xbfb8aa3b, v151
	v_exp_f32_e32 v152, v152
	v_mul_f32_e32 v153, 0xbfb8aa3b, v153
	v_exp_f32_e32 v154, v154
	v_mul_f32_e32 v155, 0xbfb8aa3b, v155
	v_exp_f32_e32 v151, v151
	v_exp_f32_e32 v153, v153
	v_exp_f32_e32 v155, v155
	v_add_f32_e32 v148, 1.0, v148
	v_add_f32_e32 v149, 1.0, v149
	v_add_f32_e32 v152, 1.0, v152
	v_add_f32_e32 v154, 1.0, v154
	v_rcp_f32_e32 v148, v148
	v_rcp_f32_e32 v149, v149
	v_add_f32_e32 v151, 1.0, v151
	v_rcp_f32_e32 v152, v152
	v_add_f32_e32 v153, 1.0, v153
	v_rcp_f32_e32 v154, v154
	v_add_f32_e32 v155, 1.0, v155
	v_rcp_f32_e32 v151, v151
	v_rcp_f32_e32 v153, v153
	v_rcp_f32_e32 v155, v155
	v_cvt_pk_bf16_f32 v148, v148, v149
	v_cvt_pk_bf16_f32 v149, v152, v154
	v_add_co_u32_e32 v152, vcc, s83, v136
	v_cvt_pk_bf16_f32 v150, v150, v151
	v_cvt_pk_bf16_f32 v151, v153, v155
	v_addc_co_u32_e32 v153, vcc, 0, v137, vcc
	global_store_dwordx4 v[152:153], v[148:151], off
	v_fma_f32 v152, v110, v146, v134
	v_fma_f32 v154, v111, v146, v135
	v_fma_f32 v149, v104, v146, v128
	v_mul_f32_e32 v149, 0xbfb8aa3b, v149
	v_exp_f32_e32 v149, v149
	v_fma_f32 v148, v108, v146, v132
	v_mul_f32_e32 v148, 0xbfb8aa3b, v148
	v_fma_f32 v151, v105, v146, v129
	v_add_f32_e32 v149, 1.0, v149
	v_rcp_f32_e32 v150, v149
	v_fma_f32 v149, v109, v146, v133
	v_mul_f32_e32 v149, 0xbfb8aa3b, v149
	v_mul_f32_e32 v152, 0xbfb8aa3b, v152
	v_fma_f32 v153, v106, v146, v130
	v_mul_f32_e32 v154, 0xbfb8aa3b, v154
	v_fma_f32 v155, v107, v146, v131
	v_exp_f32_e32 v148, v148
	v_exp_f32_e32 v149, v149
	v_mul_f32_e32 v151, 0xbfb8aa3b, v151
	v_exp_f32_e32 v152, v152
	v_mul_f32_e32 v153, 0xbfb8aa3b, v153
	v_exp_f32_e32 v154, v154
	v_mul_f32_e32 v155, 0xbfb8aa3b, v155
	v_exp_f32_e32 v151, v151
	v_exp_f32_e32 v153, v153
	v_exp_f32_e32 v155, v155
	v_add_f32_e32 v148, 1.0, v148
	v_add_f32_e32 v149, 1.0, v149
	v_add_f32_e32 v152, 1.0, v152
	v_add_f32_e32 v154, 1.0, v154
	v_rcp_f32_e32 v148, v148
	v_rcp_f32_e32 v149, v149
	v_add_f32_e32 v151, 1.0, v151
	v_rcp_f32_e32 v152, v152
	v_add_f32_e32 v153, 1.0, v153
	v_rcp_f32_e32 v154, v154
	v_add_f32_e32 v155, 1.0, v155
	v_rcp_f32_e32 v151, v151
	v_rcp_f32_e32 v153, v153
	v_rcp_f32_e32 v155, v155
	v_cvt_pk_bf16_f32 v148, v148, v149
	v_cvt_pk_bf16_f32 v149, v152, v154
	v_add_co_u32_e32 v152, vcc, s10, v136
	v_cvt_pk_bf16_f32 v150, v150, v151
	v_cvt_pk_bf16_f32 v151, v153, v155
	v_addc_co_u32_e32 v153, vcc, 0, v137, vcc
	global_store_dwordx4 v[152:153], v[148:151], off
	v_fma_f32 v152, v102, v143, v134
	v_fma_f32 v154, v103, v143, v135
	v_fma_f32 v149, v96, v143, v128
	v_mul_f32_e32 v149, 0xbfb8aa3b, v149
	v_exp_f32_e32 v149, v149
	v_fma_f32 v148, v100, v143, v132
	v_mul_f32_e32 v148, 0xbfb8aa3b, v148
	v_fma_f32 v151, v97, v143, v129
; __device__ __forceinline__ u32x4 pack8(const f32x4& a, const f32x4& b) { u32x4 w; w.x = pk2(a[0], a[1]); w.y = pk2(a[2], a[3]); w.z = pk2(b[0], b[1]); w.w = pk2(b[2], b[3]); return w; }
; __device__ __forceinline__ float sigm(float x) { return __builtin_amdgcn_rcpf(1.0f + __builtin_amdgcn_exp2f(x * -1.4426950408889634f)); }
;     __device__ __forceinline__ void operator()(const f32x4 (&acc)[2][2][4][2], const Unit& u, int wr, int wc, int fr, int fq) const {
;     ...
;             for (int bj = 0; bj < 2; ++bj) {
;                 const f32x4 bv0 = *(const f32x4*)(gb + br * 1024 + col0 + 128 * bj), bv1 = *(const f32x4*)(gb + br * 1024 + col0 + 128 * bj + 4);
; #pragma unroll
;                 for (int ai = 0; ai < 2; ++ai)
; #pragma unroll
;                     for (int m = 0; m < 4; ++m) {
;                         const f32x4 a0 = acc[ai][bj][m][0] * rx[ai][m] + bv0, a1 = acc[ai][bj][m][1] * rx[ai][m] + bv1; f32x4 o0, o1;
; #pragma unroll
;                         for (int e = 0; e < 4; ++e) { o0[e] = sigm(a0[e]); o1[e] = sigm(a1[e]); }
;                         *(u32x4*)(tmpb + ((ai * 4 + m) * 2 + bj) * 8192 + voff) = pack8(o0, o1); }
;                 asm volatile("" ::: "memory"); }
	v_add_f32_e32 v149, 1.0, v149
	v_rcp_f32_e32 v150, v149
	v_fma_f32 v149, v101, v143, v133
	v_mul_f32_e32 v149, 0xbfb8aa3b, v149
	v_mul_f32_e32 v152, 0xbfb8aa3b, v152
	v_fma_f32 v153, v98, v143, v130
	v_mul_f32_e32 v154, 0xbfb8aa3b, v154
	v_fma_f32 v155, v99, v143, v131
	v_exp_f32_e32 v148, v148
	v_exp_f32_e32 v149, v149
	v_mul_f32_e32 v151, 0xbfb8aa3b, v151
	v_exp_f32_e32 v152, v152
	v_mul_f32_e32 v153, 0xbfb8aa3b, v153
	v_exp_f32_e32 v154, v154
	v_mul_f32_e32 v155, 0xbfb8aa3b, v155
	v_exp_f32_e32 v151, v151
	v_exp_f32_e32 v153, v153
	v_exp_f32_e32 v155, v155
	v_add_f32_e32 v148, 1.0, v148
	v_add_f32_e32 v149, 1.0, v149
	v_add_f32_e32 v152, 1.0, v152
	v_add_f32_e32 v154, 1.0, v154
	v_rcp_f32_e32 v148, v148
	v_rcp_f32_e32 v149, v149
	v_add_f32_e32 v151, 1.0, v151
	v_rcp_f32_e32 v152, v152
	v_add_f32_e32 v153, 1.0, v153
	v_rcp_f32_e32 v154, v154
	v_add_f32_e32 v155, 1.0, v155
	v_rcp_f32_e32 v151, v151
	v_rcp_f32_e32 v153, v153
	v_rcp_f32_e32 v155, v155
	s_mov_b32 s10, 0xc000
	v_cvt_pk_bf16_f32 v148, v148, v149
	v_cvt_pk_bf16_f32 v149, v152, v154
	v_add_co_u32_e32 v152, vcc, s10, v136
	v_cvt_pk_bf16_f32 v150, v150, v151
	v_cvt_pk_bf16_f32 v151, v153, v155
	v_addc_co_u32_e32 v153, vcc, 0, v137, vcc
	global_store_dwordx4 v[152:153], v[148:151], off
	v_fma_f32 v152, v62, v144, v134
	v_fma_f32 v154, v63, v144, v135
	v_fma_f32 v149, v56, v144, v128
	v_mul_f32_e32 v149, 0xbfb8aa3b, v149
	v_exp_f32_e32 v149, v149
	v_fma_f32 v148, v60, v144, v132
	v_mul_f32_e32 v148, 0xbfb8aa3b, v148
	v_fma_f32 v151, v57, v144, v129
	v_add_f32_e32 v149, 1.0, v149
	v_rcp_f32_e32 v150, v149
	v_fma_f32 v149, v61, v144, v133
	v_mul_f32_e32 v149, 0xbfb8aa3b, v149
	v_mul_f32_e32 v152, 0xbfb8aa3b, v152
	v_fma_f32 v153, v58, v144, v130
	v_mul_f32_e32 v154, 0xbfb8aa3b, v154
	v_fma_f32 v155, v59, v144, v131
	v_exp_f32_e32 v148, v148
	v_exp_f32_e32 v149, v149
	v_mul_f32_e32 v151, 0xbfb8aa3b, v151
	v_exp_f32_e32 v152, v152
	v_mul_f32_e32 v153, 0xbfb8aa3b, v153
	v_exp_f32_e32 v154, v154
	v_mul_f32_e32 v155, 0xbfb8aa3b, v155
	v_exp_f32_e32 v151, v151
	v_exp_f32_e32 v153, v153
	v_exp_f32_e32 v155, v155
	v_add_f32_e32 v148, 1.0, v148
	v_add_f32_e32 v149, 1.0, v149
	v_add_f32_e32 v152, 1.0, v152
	v_add_f32_e32 v154, 1.0, v154
	v_rcp_f32_e32 v148, v148
	v_rcp_f32_e32 v149, v149
	v_add_f32_e32 v151, 1.0, v151
	v_rcp_f32_e32 v152, v152
	v_add_f32_e32 v153, 1.0, v153
	v_rcp_f32_e32 v154, v154
	v_add_f32_e32 v155, 1.0, v155
	v_rcp_f32_e32 v151, v151
	v_rcp_f32_e32 v153, v153
	v_rcp_f32_e32 v155, v155
	v_cvt_pk_bf16_f32 v148, v148, v149
	v_cvt_pk_bf16_f32 v149, v152, v154
	v_add_co_u32_e32 v152, vcc, s4, v136
	v_cvt_pk_bf16_f32 v150, v150, v151
	v_cvt_pk_bf16_f32 v151, v153, v155
	v_addc_co_u32_e32 v153, vcc, 0, v137, vcc
	global_store_dwordx4 v[152:153], v[148:151], off
	v_fma_f32 v152, v54, v142, v134
	v_fma_f32 v154, v55, v142, v135
	v_fma_f32 v149, v48, v142, v128
	v_mul_f32_e32 v149, 0xbfb8aa3b, v149
	v_exp_f32_e32 v149, v149
	v_fma_f32 v148, v52, v142, v132
	v_mul_f32_e32 v148, 0xbfb8aa3b, v148
	v_fma_f32 v151, v49, v142, v129
	v_add_f32_e32 v149, 1.0, v149
	v_rcp_f32_e32 v150, v149
	v_fma_f32 v149, v53, v142, v133
	v_mul_f32_e32 v149, 0xbfb8aa3b, v149
	v_mul_f32_e32 v152, 0xbfb8aa3b, v152
	v_fma_f32 v153, v50, v142, v130
	v_mul_f32_e32 v154, 0xbfb8aa3b, v154
	v_fma_f32 v155, v51, v142, v131
	v_exp_f32_e32 v148, v148
	v_exp_f32_e32 v149, v149
	v_mul_f32_e32 v151, 0xbfb8aa3b, v151
	v_exp_f32_e32 v152, v152
	v_mul_f32_e32 v153, 0xbfb8aa3b, v153
	v_exp_f32_e32 v154, v154
	v_mul_f32_e32 v155, 0xbfb8aa3b, v155
	v_exp_f32_e32 v151, v151
	v_exp_f32_e32 v153, v153
	v_exp_f32_e32 v155, v155
	v_add_f32_e32 v148, 1.0, v148
	v_add_f32_e32 v149, 1.0, v149
	v_add_f32_e32 v152, 1.0, v152
	v_add_f32_e32 v154, 1.0, v154
	v_rcp_f32_e32 v148, v148
	v_rcp_f32_e32 v149, v149
	v_add_f32_e32 v151, 1.0, v151
	v_rcp_f32_e32 v152, v152
	v_add_f32_e32 v153, 1.0, v153
	v_rcp_f32_e32 v154, v154
	v_add_f32_e32 v155, 1.0, v155
	v_rcp_f32_e32 v151, v151
	v_rcp_f32_e32 v153, v153
	v_rcp_f32_e32 v155, v155
	v_cvt_pk_bf16_f32 v148, v148, v149
	v_cvt_pk_bf16_f32 v149, v152, v154
	v_add_co_u32_e32 v152, vcc, s6, v136
	v_cvt_pk_bf16_f32 v150, v150, v151
	v_cvt_pk_bf16_f32 v151, v153, v155
	v_addc_co_u32_e32 v153, vcc, 0, v137, vcc
	global_store_dwordx4 v[152:153], v[148:151], off
	v_fma_f32 v152, v46, v141, v134
	v_fma_f32 v154, v47, v141, v135
	v_fma_f32 v149, v40, v141, v128
	v_mul_f32_e32 v149, 0xbfb8aa3b, v149
	v_exp_f32_e32 v149, v149
	v_fma_f32 v148, v44, v141, v132
	v_mul_f32_e32 v148, 0xbfb8aa3b, v148
	v_fma_f32 v151, v41, v141, v129
	v_add_f32_e32 v149, 1.0, v149
	v_rcp_f32_e32 v150, v149
	v_fma_f32 v149, v45, v141, v133
	v_mul_f32_e32 v149, 0xbfb8aa3b, v149
	v_mul_f32_e32 v152, 0xbfb8aa3b, v152
	v_fma_f32 v153, v42, v141, v130
	v_mul_f32_e32 v154, 0xbfb8aa3b, v154
	v_fma_f32 v155, v43, v141, v131
	v_exp_f32_e32 v148, v148
	v_exp_f32_e32 v149, v149
	v_mul_f32_e32 v151, 0xbfb8aa3b, v151
	v_exp_f32_e32 v152, v152
	v_mul_f32_e32 v153, 0xbfb8aa3b, v153
	v_exp_f32_e32 v154, v154
	v_mul_f32_e32 v155, 0xbfb8aa3b, v155
	v_exp_f32_e32 v151, v151
	v_exp_f32_e32 v153, v153
	v_exp_f32_e32 v155, v155
	v_add_f32_e32 v148, 1.0, v148
	v_add_f32_e32 v149, 1.0, v149
	v_add_f32_e32 v152, 1.0, v152
	v_add_f32_e32 v154, 1.0, v154
	v_fma_f32 v128, v32, v140, v128
	v_rcp_f32_e32 v148, v148
	v_rcp_f32_e32 v149, v149
	v_add_f32_e32 v151, 1.0, v151
	v_rcp_f32_e32 v152, v152
	v_add_f32_e32 v153, 1.0, v153
	v_rcp_f32_e32 v154, v154
	v_add_f32_e32 v155, 1.0, v155
	v_mul_f32_e32 v128, 0xbfb8aa3b, v128
	v_fma_f32 v129, v33, v140, v129
	v_rcp_f32_e32 v151, v151
	v_rcp_f32_e32 v153, v153
	v_rcp_f32_e32 v155, v155
	v_exp_f32_e32 v128, v128
; __device__ __forceinline__ u32x4 pack8(const f32x4& a, const f32x4& b) { u32x4 w; w.x = pk2(a[0], a[1]); w.y = pk2(a[2], a[3]); w.z = pk2(b[0], b[1]); w.w = pk2(b[2], b[3]); return w; }
; __device__ __forceinline__ float sigm(float x) { return __builtin_amdgcn_rcpf(1.0f + __builtin_amdgcn_exp2f(x * -1.4426950408889634f)); }
;     __device__ __forceinline__ void operator()(const f32x4 (&acc)[2][2][4][2], const Unit& u, int wr, int wc, int fr, int fq) const {
;     ...
;             for (int bj = 0; bj < 2; ++bj) {
;                 const f32x4 bv0 = *(const f32x4*)(gb + br * 1024 + col0 + 128 * bj), bv1 = *(const f32x4*)(gb + br * 1024 + col0 + 128 * bj + 4);
; #pragma unroll
;                 for (int ai = 0; ai < 2; ++ai)
; #pragma unroll
;                     for (int m = 0; m < 4; ++m) {
;                         const f32x4 a0 = acc[ai][bj][m][0] * rx[ai][m] + bv0, a1 = acc[ai][bj][m][1] * rx[ai][m] + bv1; f32x4 o0, o1;
; #pragma unroll
;                         for (int e = 0; e < 4; ++e) { o0[e] = sigm(a0[e]); o1[e] = sigm(a1[e]); }
;                         *(u32x4*)(tmpb + ((ai * 4 + m) * 2 + bj) * 8192 + voff) = pack8(o0, o1); }
;                 asm volatile("" ::: "memory"); }
	v_mul_f32_e32 v129, 0xbfb8aa3b, v129
	v_fma_f32 v130, v34, v140, v130
	v_exp_f32_e32 v129, v129
	v_mul_f32_e32 v130, 0xbfb8aa3b, v130
	v_exp_f32_e32 v130, v130
	v_cvt_pk_bf16_f32 v148, v148, v149
	v_cvt_pk_bf16_f32 v149, v152, v154
	v_add_co_u32_e32 v152, vcc, s79, v136
	v_cvt_pk_bf16_f32 v150, v150, v151
	v_cvt_pk_bf16_f32 v151, v153, v155
	v_addc_co_u32_e32 v153, vcc, 0, v137, vcc
	v_add_f32_e32 v128, 1.0, v128
	global_store_dwordx4 v[152:153], v[148:151], off
	v_fma_f32 v132, v36, v140, v132
	v_add_f32_e32 v129, 1.0, v129
	v_rcp_f32_e32 v148, v128
	v_fma_f32 v128, v37, v140, v133
	v_mul_f32_e32 v132, 0xbfb8aa3b, v132
	v_mul_f32_e32 v128, 0xbfb8aa3b, v128
	v_rcp_f32_e32 v133, v129
	v_fma_f32 v129, v38, v140, v134
	v_add_f32_e32 v130, 1.0, v130
	v_fmac_f32_e32 v135, v39, v140
	v_fmac_f32_e32 v131, v35, v140
	v_exp_f32_e32 v132, v132
	v_exp_f32_e32 v128, v128
	v_mul_f32_e32 v129, 0xbfb8aa3b, v129
	v_rcp_f32_e32 v134, v130
	v_mul_f32_e32 v130, 0xbfb8aa3b, v135
	v_mul_f32_e32 v131, 0xbfb8aa3b, v131
	v_exp_f32_e32 v129, v129
	v_exp_f32_e32 v130, v130
	v_exp_f32_e32 v131, v131
	v_add_f32_e32 v132, 1.0, v132
	v_add_f32_e32 v128, 1.0, v128
	v_rcp_f32_e32 v132, v132
	v_rcp_f32_e32 v128, v128
	v_add_f32_e32 v129, 1.0, v129
	v_add_f32_e32 v130, 1.0, v130
	v_add_f32_e32 v131, 1.0, v131
	v_rcp_f32_e32 v129, v129
	v_rcp_f32_e32 v130, v130
	v_rcp_f32_e32 v131, v131
	v_cvt_pk_bf16_f32 v128, v132, v128
	v_add_co_u32_e32 v132, vcc, s87, v136
	v_cvt_pk_bf16_f32 v129, v129, v130
	v_cvt_pk_bf16_f32 v130, v148, v133
	v_cvt_pk_bf16_f32 v131, v134, v131
	v_addc_co_u32_e32 v133, vcc, 0, v137, vcc
	global_store_dwordx4 v[132:133], v[128:131], off
	global_load_dwordx4 v[128:131], v[138:139], off offset:528
	global_load_dwordx4 v[132:135], v[138:139], off offset:512
	s_movk_i32 s10, 0x6000
	s_waitcnt vmcnt(1)
	v_fma_f32 v149, v89, v147, v129
	v_mul_f32_e32 v149, 0xbfb8aa3b, v149
	v_exp_f32_e32 v149, v149
	s_waitcnt vmcnt(0)
	v_fma_f32 v138, v92, v147, v132
	v_fma_f32 v148, v93, v147, v133
	v_mul_f32_e32 v138, 0xbfb8aa3b, v138
	v_add_f32_e32 v149, 1.0, v149
	v_fma_f32 v139, v88, v147, v128
	v_mul_f32_e32 v148, 0xbfb8aa3b, v148
	v_rcp_f32_e32 v150, v149
	v_fma_f32 v149, v94, v147, v134
	v_fma_f32 v151, v90, v147, v130
	v_fma_f32 v152, v95, v147, v135
	v_fma_f32 v147, v91, v147, v131
	v_exp_f32_e32 v138, v138
	v_mul_f32_e32 v139, 0xbfb8aa3b, v139
	v_exp_f32_e32 v148, v148
	v_mul_f32_e32 v149, 0xbfb8aa3b, v149
	v_mul_f32_e32 v151, 0xbfb8aa3b, v151
	v_mul_f32_e32 v152, 0xbfb8aa3b, v152
	v_mul_f32_e32 v147, 0xbfb8aa3b, v147
	v_exp_f32_e32 v139, v139
	v_exp_f32_e32 v149, v149
	v_exp_f32_e32 v151, v151
	v_exp_f32_e32 v152, v152
	v_exp_f32_e32 v147, v147
	v_add_f32_e32 v138, 1.0, v138
	v_add_f32_e32 v148, 1.0, v148
	v_rcp_f32_e32 v138, v138
	v_add_f32_e32 v139, 1.0, v139
	v_rcp_f32_e32 v148, v148
	v_add_f32_e32 v149, 1.0, v149
	v_add_f32_e32 v151, 1.0, v151
	v_add_f32_e32 v152, 1.0, v152
	v_add_f32_e32 v147, 1.0, v147
	v_rcp_f32_e32 v139, v139
	v_rcp_f32_e32 v149, v149
	v_rcp_f32_e32 v151, v151
	v_rcp_f32_e32 v152, v152
	v_rcp_f32_e32 v147, v147
	v_cvt_pk_bf16_f32 v148, v138, v148
	v_add_co_u32_e32 v138, vcc, s82, v136
	v_cvt_pk_bf16_f32 v149, v149, v152
	v_cvt_pk_bf16_f32 v150, v139, v150
	v_cvt_pk_bf16_f32 v151, v151, v147
	v_addc_co_u32_e32 v139, vcc, 0, v137, vcc
	global_store_dwordx4 v[138:139], v[148:151], off
	v_fma_f32 v138, v84, v145, v132
	v_fma_f32 v147, v85, v145, v133
	v_fma_f32 v148, v81, v145, v129
	v_mul_f32_e32 v148, 0xbfb8aa3b, v148
	v_exp_f32_e32 v148, v148
	v_mul_f32_e32 v138, 0xbfb8aa3b, v138
	v_mul_f32_e32 v147, 0xbfb8aa3b, v147
	v_exp_f32_e32 v138, v138
	v_add_f32_e32 v148, 1.0, v148
	v_rcp_f32_e32 v150, v148
	v_fma_f32 v148, v86, v145, v134
	v_mul_f32_e32 v148, 0xbfb8aa3b, v148
	v_exp_f32_e32 v148, v148
	v_exp_f32_e32 v147, v147
	v_fma_f32 v139, v80, v145, v128
	v_add_f32_e32 v138, 1.0, v138
	v_add_f32_e32 v148, 1.0, v148
	v_rcp_f32_e32 v149, v148
	v_fma_f32 v148, v82, v145, v130
	v_mul_f32_e32 v148, 0xbfb8aa3b, v148
	v_exp_f32_e32 v148, v148
	v_mul_f32_e32 v139, 0xbfb8aa3b, v139
	v_add_f32_e32 v147, 1.0, v147
	v_rcp_f32_e32 v138, v138
	v_add_f32_e32 v148, 1.0, v148
	v_rcp_f32_e32 v151, v148
	v_fma_f32 v148, v87, v145, v135
	v_mul_f32_e32 v148, 0xbfb8aa3b, v148
	v_fma_f32 v145, v83, v145, v131
	v_exp_f32_e32 v148, v148
	v_mul_f32_e32 v145, 0xbfb8aa3b, v145
	v_exp_f32_e32 v139, v139
	v_rcp_f32_e32 v147, v147
	v_exp_f32_e32 v145, v145
	v_add_f32_e32 v148, 1.0, v148
	v_add_f32_e32 v139, 1.0, v139
	v_rcp_f32_e32 v152, v148
	v_add_f32_e32 v145, 1.0, v145
	v_cvt_pk_bf16_f32 v148, v138, v147
	v_fma_f32 v147, v73, v146, v129
	v_rcp_f32_e32 v139, v139
	v_rcp_f32_e32 v145, v145
	v_mul_f32_e32 v147, 0xbfb8aa3b, v147
	v_exp_f32_e32 v147, v147
	v_add_co_u32_e32 v138, vcc, s10, v136
	v_cvt_pk_bf16_f32 v149, v149, v152
	v_cvt_pk_bf16_f32 v150, v139, v150
	v_cvt_pk_bf16_f32 v151, v151, v145
	v_addc_co_u32_e32 v139, vcc, 0, v137, vcc
	global_store_dwordx4 v[138:139], v[148:151], off
	v_fma_f32 v138, v76, v146, v132
	v_fma_f32 v145, v77, v146, v133
	v_add_f32_e32 v147, 1.0, v147
	v_mul_f32_e32 v138, 0xbfb8aa3b, v138
	v_fma_f32 v139, v72, v146, v128
	v_mul_f32_e32 v145, 0xbfb8aa3b, v145
	v_rcp_f32_e32 v148, v147
	v_fma_f32 v147, v78, v146, v134
	v_fma_f32 v149, v74, v146, v130
	v_fma_f32 v150, v79, v146, v135
	v_fma_f32 v146, v75, v146, v131
	v_exp_f32_e32 v138, v138
	v_mul_f32_e32 v139, 0xbfb8aa3b, v139
	v_exp_f32_e32 v145, v145
	v_mul_f32_e32 v147, 0xbfb8aa3b, v147
	v_mul_f32_e32 v149, 0xbfb8aa3b, v149
	v_mul_f32_e32 v150, 0xbfb8aa3b, v150
	v_mul_f32_e32 v146, 0xbfb8aa3b, v146
	v_exp_f32_e32 v139, v139
	v_exp_f32_e32 v147, v147
	v_exp_f32_e32 v149, v149
; __device__ __forceinline__ u32x4 pack8(const f32x4& a, const f32x4& b) { u32x4 w; w.x = pk2(a[0], a[1]); w.y = pk2(a[2], a[3]); w.z = pk2(b[0], b[1]); w.w = pk2(b[2], b[3]); return w; }
; __device__ __forceinline__ float sigm(float x) { return __builtin_amdgcn_rcpf(1.0f + __builtin_amdgcn_exp2f(x * -1.4426950408889634f)); }
;     __device__ __forceinline__ void operator()(const f32x4 (&acc)[2][2][4][2], const Unit& u, int wr, int wc, int fr, int fq) const {
;     ...
;             for (int bj = 0; bj < 2; ++bj) {
;                 const f32x4 bv0 = *(const f32x4*)(gb + br * 1024 + col0 + 128 * bj), bv1 = *(const f32x4*)(gb + br * 1024 + col0 + 128 * bj + 4);
; #pragma unroll
;                 for (int ai = 0; ai < 2; ++ai)
; #pragma unroll
;                     for (int m = 0; m < 4; ++m) {
;                         const f32x4 a0 = acc[ai][bj][m][0] * rx[ai][m] + bv0, a1 = acc[ai][bj][m][1] * rx[ai][m] + bv1; f32x4 o0, o1;
; #pragma unroll
;                         for (int e = 0; e < 4; ++e) { o0[e] = sigm(a0[e]); o1[e] = sigm(a1[e]); }
;                         *(u32x4*)(tmpb + ((ai * 4 + m) * 2 + bj) * 8192 + voff) = pack8(o0, o1); }
;                 asm volatile("" ::: "memory"); }
	v_exp_f32_e32 v150, v150
	v_exp_f32_e32 v146, v146
	v_add_f32_e32 v138, 1.0, v138
	v_add_f32_e32 v145, 1.0, v145
	v_rcp_f32_e32 v138, v138
	v_add_f32_e32 v139, 1.0, v139
	v_rcp_f32_e32 v145, v145
	v_add_f32_e32 v147, 1.0, v147
	v_add_f32_e32 v149, 1.0, v149
	v_add_f32_e32 v150, 1.0, v150
	v_add_f32_e32 v146, 1.0, v146
	v_rcp_f32_e32 v139, v139
	v_rcp_f32_e32 v147, v147
	v_rcp_f32_e32 v149, v149
	v_rcp_f32_e32 v150, v150
	v_rcp_f32_e32 v151, v146
	s_mov_b32 s10, 0xa000
	v_cvt_pk_bf16_f32 v146, v138, v145
	v_add_co_u32_e32 v138, vcc, s10, v136
	v_cvt_pk_bf16_f32 v147, v147, v150
	v_cvt_pk_bf16_f32 v148, v139, v148
	v_cvt_pk_bf16_f32 v149, v149, v151
	v_addc_co_u32_e32 v139, vcc, 0, v137, vcc
	global_store_dwordx4 v[138:139], v[146:149], off
	v_fma_f32 v138, v68, v143, v132
	v_fma_f32 v145, v69, v143, v133
	v_fma_f32 v146, v65, v143, v129
	v_mul_f32_e32 v146, 0xbfb8aa3b, v146
	v_exp_f32_e32 v146, v146
	v_mul_f32_e32 v138, 0xbfb8aa3b, v138
	v_mul_f32_e32 v145, 0xbfb8aa3b, v145
	v_exp_f32_e32 v138, v138
	v_add_f32_e32 v146, 1.0, v146
	v_rcp_f32_e32 v148, v146
	v_fma_f32 v146, v70, v143, v134
	v_mul_f32_e32 v146, 0xbfb8aa3b, v146
	v_exp_f32_e32 v146, v146
	v_exp_f32_e32 v145, v145
	v_fma_f32 v139, v64, v143, v128
	v_add_f32_e32 v138, 1.0, v138
	v_add_f32_e32 v146, 1.0, v146
	v_rcp_f32_e32 v147, v146
	v_fma_f32 v146, v66, v143, v130
	v_mul_f32_e32 v146, 0xbfb8aa3b, v146
	v_exp_f32_e32 v146, v146
	v_mul_f32_e32 v139, 0xbfb8aa3b, v139
	v_add_f32_e32 v145, 1.0, v145
	v_rcp_f32_e32 v138, v138
	v_add_f32_e32 v146, 1.0, v146
	v_rcp_f32_e32 v149, v146
	v_fma_f32 v146, v71, v143, v135
	v_mul_f32_e32 v146, 0xbfb8aa3b, v146
	v_fma_f32 v143, v67, v143, v131
	v_exp_f32_e32 v146, v146
	v_mul_f32_e32 v143, 0xbfb8aa3b, v143
	v_exp_f32_e32 v139, v139
	v_rcp_f32_e32 v145, v145
	v_exp_f32_e32 v143, v143
	v_add_f32_e32 v146, 1.0, v146
	v_add_f32_e32 v139, 1.0, v139
	v_rcp_f32_e32 v150, v146
	v_add_f32_e32 v143, 1.0, v143
	v_cvt_pk_bf16_f32 v146, v138, v145
	v_fma_f32 v145, v25, v144, v129
	v_rcp_f32_e32 v139, v139
	v_rcp_f32_e32 v143, v143
	v_mul_f32_e32 v145, 0xbfb8aa3b, v145
	v_exp_f32_e32 v145, v145
	v_add_co_u32_e32 v138, vcc, s98, v136
	v_cvt_pk_bf16_f32 v147, v147, v150
	v_cvt_pk_bf16_f32 v148, v139, v148
	v_cvt_pk_bf16_f32 v149, v149, v143
	v_addc_co_u32_e32 v139, vcc, 0, v137, vcc
	global_store_dwordx4 v[138:139], v[146:149], off
	v_fma_f32 v138, v28, v144, v132
	v_fma_f32 v143, v29, v144, v133
	v_add_f32_e32 v145, 1.0, v145
	v_mul_f32_e32 v138, 0xbfb8aa3b, v138
	v_fma_f32 v139, v24, v144, v128
	v_mul_f32_e32 v143, 0xbfb8aa3b, v143
	v_rcp_f32_e32 v146, v145
	v_fma_f32 v145, v30, v144, v134
	v_fma_f32 v147, v26, v144, v130
	v_fma_f32 v148, v31, v144, v135
	v_fma_f32 v144, v27, v144, v131
	v_exp_f32_e32 v138, v138
	v_mul_f32_e32 v139, 0xbfb8aa3b, v139
	v_exp_f32_e32 v143, v143
	v_mul_f32_e32 v145, 0xbfb8aa3b, v145
	v_mul_f32_e32 v147, 0xbfb8aa3b, v147
	v_mul_f32_e32 v148, 0xbfb8aa3b, v148
	v_mul_f32_e32 v144, 0xbfb8aa3b, v144
	v_exp_f32_e32 v139, v139
	v_exp_f32_e32 v145, v145
	v_exp_f32_e32 v147, v147
	v_exp_f32_e32 v148, v148
	v_exp_f32_e32 v144, v144
	v_add_f32_e32 v138, 1.0, v138
	v_add_f32_e32 v143, 1.0, v143
	v_rcp_f32_e32 v138, v138
	v_add_f32_e32 v139, 1.0, v139
	v_rcp_f32_e32 v143, v143
	v_add_f32_e32 v145, 1.0, v145
	v_add_f32_e32 v147, 1.0, v147
	v_add_f32_e32 v148, 1.0, v148
	v_add_f32_e32 v144, 1.0, v144
	v_rcp_f32_e32 v139, v139
	v_rcp_f32_e32 v145, v145
	v_rcp_f32_e32 v147, v147
	v_rcp_f32_e32 v148, v148
	v_rcp_f32_e32 v149, v144
	v_cvt_pk_bf16_f32 v144, v138, v143
	v_add_co_u32_e32 v138, vcc, s5, v136
	v_cvt_pk_bf16_f32 v145, v145, v148
	v_cvt_pk_bf16_f32 v146, v139, v146
	v_cvt_pk_bf16_f32 v147, v147, v149
	v_addc_co_u32_e32 v139, vcc, 0, v137, vcc
	global_store_dwordx4 v[138:139], v[144:147], off
	v_fma_f32 v138, v20, v142, v132
	v_fma_f32 v143, v21, v142, v133
	v_mul_f32_e32 v138, 0xbfb8aa3b, v138
	v_fma_f32 v139, v16, v142, v128
	v_mul_f32_e32 v143, 0xbfb8aa3b, v143
	v_fma_f32 v144, v17, v142, v129
	v_fma_f32 v145, v22, v142, v134
	v_fma_f32 v146, v18, v142, v130
	v_fma_f32 v147, v23, v142, v135
	v_fma_f32 v142, v19, v142, v131
	v_exp_f32_e32 v138, v138
; __device__ __forceinline__ u32x4 pack8(const f32x4& a, const f32x4& b) { u32x4 w; w.x = pk2(a[0], a[1]); w.y = pk2(a[2], a[3]); w.z = pk2(b[0], b[1]); w.w = pk2(b[2], b[3]); return w; }
; __device__ __forceinline__ float sigm(float x) { return __builtin_amdgcn_rcpf(1.0f + __builtin_amdgcn_exp2f(x * -1.4426950408889634f)); }
;     __device__ __forceinline__ void operator()(const f32x4 (&acc)[2][2][4][2], const Unit& u, int wr, int wc, int fr, int fq) const {
;     ...
;             for (int bj = 0; bj < 2; ++bj) {
;                 const f32x4 bv0 = *(const f32x4*)(gb + br * 1024 + col0 + 128 * bj), bv1 = *(const f32x4*)(gb + br * 1024 + col0 + 128 * bj + 4);
; #pragma unroll
;                 for (int ai = 0; ai < 2; ++ai)
; #pragma unroll
;                     for (int m = 0; m < 4; ++m) {
;                         const f32x4 a0 = acc[ai][bj][m][0] * rx[ai][m] + bv0, a1 = acc[ai][bj][m][1] * rx[ai][m] + bv1; f32x4 o0, o1;
; #pragma unroll
;                         for (int e = 0; e < 4; ++e) { o0[e] = sigm(a0[e]); o1[e] = sigm(a1[e]); }
;                         *(u32x4*)(tmpb + ((ai * 4 + m) * 2 + bj) * 8192 + voff) = pack8(o0, o1); }
;                 asm volatile("" ::: "memory"); }
	v_mul_f32_e32 v139, 0xbfb8aa3b, v139
	v_exp_f32_e32 v143, v143
	v_mul_f32_e32 v144, 0xbfb8aa3b, v144
	v_mul_f32_e32 v145, 0xbfb8aa3b, v145
	v_mul_f32_e32 v146, 0xbfb8aa3b, v146
	v_mul_f32_e32 v147, 0xbfb8aa3b, v147
	v_mul_f32_e32 v142, 0xbfb8aa3b, v142
	v_exp_f32_e32 v139, v139
	v_exp_f32_e32 v144, v144
	v_exp_f32_e32 v145, v145
	v_exp_f32_e32 v146, v146
	v_exp_f32_e32 v147, v147
	v_exp_f32_e32 v142, v142
	v_add_f32_e32 v138, 1.0, v138
	v_add_f32_e32 v143, 1.0, v143
	v_rcp_f32_e32 v138, v138
	v_add_f32_e32 v139, 1.0, v139
	v_rcp_f32_e32 v143, v143
	v_add_f32_e32 v144, 1.0, v144
	v_add_f32_e32 v145, 1.0, v145
	v_add_f32_e32 v146, 1.0, v146
	v_add_f32_e32 v147, 1.0, v147
	v_add_f32_e32 v142, 1.0, v142
	v_rcp_f32_e32 v139, v139
	v_rcp_f32_e32 v144, v144
	v_rcp_f32_e32 v145, v145
	v_rcp_f32_e32 v146, v146
	v_rcp_f32_e32 v147, v147
	v_rcp_f32_e32 v148, v142
	v_cvt_pk_bf16_f32 v142, v138, v143
	v_add_co_u32_e32 v138, vcc, s7, v136
	v_cvt_pk_bf16_f32 v143, v145, v147
	v_cvt_pk_bf16_f32 v144, v139, v144
	v_cvt_pk_bf16_f32 v145, v146, v148
	v_addc_co_u32_e32 v139, vcc, 0, v137, vcc
	global_store_dwordx4 v[138:139], v[142:145], off
	v_fma_f32 v138, v12, v141, v132
	v_mul_f32_e32 v138, 0xbfb8aa3b, v138
	v_fma_f32 v143, v9, v141, v129
	v_mul_f32_e32 v143, 0xbfb8aa3b, v143
	v_exp_f32_e32 v143, v143
	v_fma_f32 v142, v13, v141, v133
	v_fma_f32 v139, v8, v141, v128
	v_mul_f32_e32 v142, 0xbfb8aa3b, v142
	v_add_f32_e32 v143, 1.0, v143
	v_rcp_f32_e32 v144, v143
	v_fma_f32 v143, v14, v141, v134
	v_fma_f32 v145, v10, v141, v130
	v_fma_f32 v146, v15, v141, v135
	v_fma_f32 v141, v11, v141, v131
	v_exp_f32_e32 v138, v138
	v_mul_f32_e32 v139, 0xbfb8aa3b, v139
	v_exp_f32_e32 v142, v142
	v_mul_f32_e32 v143, 0xbfb8aa3b, v143
	v_mul_f32_e32 v145, 0xbfb8aa3b, v145
	v_mul_f32_e32 v146, 0xbfb8aa3b, v146
	v_mul_f32_e32 v141, 0xbfb8aa3b, v141
	v_exp_f32_e32 v139, v139
	v_exp_f32_e32 v143, v143
	v_exp_f32_e32 v145, v145
	v_exp_f32_e32 v146, v146
	v_exp_f32_e32 v141, v141
	v_add_f32_e32 v138, 1.0, v138
	v_add_f32_e32 v142, 1.0, v142
	v_fma_f32 v128, v0, v140, v128
	v_rcp_f32_e32 v138, v138
	v_add_f32_e32 v139, 1.0, v139
	v_rcp_f32_e32 v142, v142
	v_add_f32_e32 v143, 1.0, v143
	v_add_f32_e32 v145, 1.0, v145
	v_add_f32_e32 v146, 1.0, v146
	v_add_f32_e32 v141, 1.0, v141
	v_mul_f32_e32 v128, 0xbfb8aa3b, v128
	v_fma_f32 v129, v1, v140, v129
	v_rcp_f32_e32 v139, v139
	v_rcp_f32_e32 v143, v143
	v_rcp_f32_e32 v145, v145
	v_rcp_f32_e32 v146, v146
	v_rcp_f32_e32 v141, v141
	v_exp_f32_e32 v128, v128
	v_mul_f32_e32 v129, 0xbfb8aa3b, v129
	v_fma_f32 v130, v2, v140, v130
	v_exp_f32_e32 v129, v129
	v_mul_f32_e32 v130, 0xbfb8aa3b, v130
	v_exp_f32_e32 v130, v130
	v_cvt_pk_bf16_f32 v142, v138, v142
	v_add_co_u32_e32 v138, vcc, s85, v136
	v_cvt_pk_bf16_f32 v143, v143, v146
	v_cvt_pk_bf16_f32 v144, v139, v144
	v_cvt_pk_bf16_f32 v145, v145, v141
	v_addc_co_u32_e32 v139, vcc, 0, v137, vcc
	v_add_f32_e32 v128, 1.0, v128
	global_store_dwordx4 v[138:139], v[142:145], off
	v_fma_f32 v132, v4, v140, v132
	v_rcp_f32_e32 v138, v128
	v_fma_f32 v128, v5, v140, v133
	v_add_f32_e32 v129, 1.0, v129
	v_mul_f32_e32 v132, 0xbfb8aa3b, v132
	v_mul_f32_e32 v128, 0xbfb8aa3b, v128
	v_rcp_f32_e32 v133, v129
	v_fma_f32 v129, v6, v140, v134
	v_add_f32_e32 v130, 1.0, v130
	v_fmac_f32_e32 v135, v7, v140
	v_fmac_f32_e32 v131, v3, v140
	v_exp_f32_e32 v132, v132
	v_exp_f32_e32 v128, v128
	v_mul_f32_e32 v129, 0xbfb8aa3b, v129
	v_rcp_f32_e32 v134, v130
	v_mul_f32_e32 v130, 0xbfb8aa3b, v135
	v_mul_f32_e32 v131, 0xbfb8aa3b, v131
	v_exp_f32_e32 v129, v129
	v_exp_f32_e32 v130, v130
	v_exp_f32_e32 v131, v131
	v_add_f32_e32 v132, 1.0, v132
	v_add_f32_e32 v128, 1.0, v128
	v_rcp_f32_e32 v132, v132
	v_rcp_f32_e32 v128, v128
	v_add_f32_e32 v129, 1.0, v129
	v_add_f32_e32 v130, 1.0, v130
	v_add_f32_e32 v131, 1.0, v131
	v_rcp_f32_e32 v129, v129
	v_rcp_f32_e32 v130, v130
	v_rcp_f32_e32 v131, v131
	v_cvt_pk_bf16_f32 v128, v132, v128
	v_add_co_u32_e32 v132, vcc, 0x1e000, v136
	v_cvt_pk_bf16_f32 v129, v129, v130
	v_cvt_pk_bf16_f32 v130, v138, v133
	v_cvt_pk_bf16_f32 v131, v134, v131
	v_addc_co_u32_e32 v133, vcc, 0, v137, vcc
	global_store_dwordx4 v[132:133], v[128:131], off

; __device__ __forceinline__ float row_rstd(const float* ssp, int row, int fq) {
;     const f32x4 t = *((const f32x4*)(ssp + (size_t)row * 16) + fq); float s = (t[0] + t[1]) + (t[2] + t[3]); s += __shfl_xor(s, 16); s += __shfl_xor(s, 32); return rsqrtf(s * (1.0f / DM) + EPS); }
;     __device__ __forceinline__ void operator()(const f32x4 (&acc)[2][2][4][2], const Unit& u, int wr, int wc, int fr, int fq) const {
;         const int row0 = u.pm * BM + wr * 64 + fr, col0 = u.pn * 128 + 32 * wc + 8 * fq, lrow0 = row0 & (SEQ - 1);
;         bf16_t* const H = (bf16_t*)(ws + WS_SLAB + (size_t)(u.pm >> 4) * SLAB + SL_H);
;         float rx[2][4];
; #pragma unroll
;         for (int ai = 0; ai < 2; ++ai)
; #pragma unroll
;             for (int m = 0; m < 4; ++m) rx[ai][m] = row_rstd(ssp, row0 + ai * HALF + m * 16, fq);
; #pragma unroll
;         for (int ai = 0; ai < 2; ++ai)
; #pragma unroll
;             for (int m = 0; m < 4; ++m) { f32x4 o[2];
; #pragma unroll
;                 for (int n = 0; n < 2; ++n) { const f32x4 a = acc[ai][0][m][n] * rx[ai][m], b = acc[ai][1][m][n] * rx[ai][m];
.LBB0_580:
	v_and_b32_e32 v129, 64, v229
	v_xor_b32_e32 v128, 16, v229
	v_add_u32_e32 v129, 64, v129
	v_cmp_lt_i32_e32 vcc, v128, v129
	v_lshl_add_u32 v130, s42, 8, v147
	v_ashrrev_i32_e32 v131, 31, v130
	v_cndmask_b32_e32 v128, v229, v128, vcc
	v_lshlrev_b32_e32 v162, 2, v128
	v_xor_b32_e32 v128, 32, v229
	v_cmp_lt_i32_e32 vcc, v128, v129
	s_mov_b32 s4, 0x358637bd
	s_ashr_i32 s29, s42, 4
	v_cndmask_b32_e32 v128, v229, v128, vcc
	v_lshlrev_b32_e32 v157, 2, v128
	v_lshlrev_b64 v[128:129], 6, v[130:131]
	v_lshl_add_u64 v[128:129], v[140:141], 0, v[128:129]
	global_load_dwordx4 v[170:173], v[128:129], off
	global_load_dwordx4 v[174:177], v[128:129], off offset:1024
	global_load_dwordx4 v[178:181], v[128:129], off offset:2048
	global_load_dwordx4 v[182:185], v[128:129], off offset:3072
	v_add_co_u32_e32 v206, vcc, s82, v128
	s_nop 1
	v_addc_co_u32_e32 v207, vcc, 0, v129, vcc
	global_load_dwordx4 v[186:189], v[206:207], off
	global_load_dwordx4 v[194:197], v[206:207], off offset:1024
	global_load_dwordx4 v[198:201], v[206:207], off offset:2048
	global_load_dwordx4 v[202:205], v[206:207], off offset:3072
	v_and_b32_e32 v155, 0xfcf, v130
	s_mul_hi_i32 s27, s29, 0x1c00000
	s_mul_i32 s29, s29, 0x1c00000
	s_add_u32 s10, s56, s29
	s_addc_u32 s11, s57, s27
	s_waitcnt vmcnt(7)
	v_mov_b32_e32 v164, v171
	v_mov_b32_e32 v165, v172
	v_mov_b32_e32 v171, v173
	v_pk_add_f32 v[164:165], v[164:165], v[170:171]
	s_waitcnt vmcnt(6)
	v_mov_b32_e32 v166, v175
	v_mov_b32_e32 v167, v176
	v_mov_b32_e32 v175, v177
	v_pk_add_f32 v[158:159], v[166:167], v[174:175]
	v_mov_b32_e32 v161, v164
	v_mov_b32_e32 v160, v158
	v_mov_b32_e32 v164, v159
	v_pk_add_f32 v[158:159], v[160:161], v[164:165]
	ds_bpermute_b32 v161, v162, v159
	ds_bpermute_b32 v160, v162, v158
	s_waitcnt lgkmcnt(0)
	v_pk_add_f32 v[158:159], v[158:159], v[160:161]
	ds_bpermute_b32 v161, v157, v159
	ds_bpermute_b32 v160, v157, v158
	s_waitcnt lgkmcnt(0)
	v_pk_add_f32 v[160:161], v[158:159], v[160:161]
	v_mov_b64_e32 v[158:159], s[4:5]
	v_pk_fma_f32 v[160:161], v[160:161], s[38:39], v[158:159] op_sel_hi:[1,0,0]
	s_nop 0
	v_mul_f32_e32 v131, 0x4b800000, v161
	v_cmp_gt_f32_e64 s[42:43], s99, v161
	v_cmp_gt_f32_e32 vcc, s99, v160
	s_nop 0
	v_cndmask_b32_e64 v131, v161, v131, s[42:43]
	v_rsq_f32_e32 v131, v131
	s_nop 0
	v_mul_f32_e32 v146, 0x45800000, v131
	v_cndmask_b32_e64 v156, v131, v146, s[42:43]
	v_mul_f32_e32 v131, 0x4b800000, v160
	v_cndmask_b32_e32 v131, v160, v131, vcc
	v_rsq_f32_e32 v131, v131
	v_pk_mul_f32 v[124:125], v[124:125], v[156:157] op_sel_hi:[1,0]
	v_pk_mul_f32 v[120:121], v[120:121], v[156:157] op_sel_hi:[1,0]
	v_mul_f32_e32 v146, 0x45800000, v131
	v_cndmask_b32_e32 v154, v131, v146, vcc
	v_pk_mul_f32 v[122:123], v[122:123], v[156:157] op_sel_hi:[1,0]
	v_pk_mul_f32 v[116:117], v[116:117], v[156:157] op_sel_hi:[1,0]
	v_pk_mul_f32 v[112:113], v[112:113], v[156:157] op_sel_hi:[1,0]
	v_pk_mul_f32 v[114:115], v[114:115], v[156:157] op_sel_hi:[1,0]
	v_pk_mul_f32 v[108:109], v[108:109], v[154:155] op_sel_hi:[1,0]
	v_pk_mul_f32 v[104:105], v[104:105], v[154:155] op_sel_hi:[1,0]
	v_pk_mul_f32 v[106:107], v[106:107], v[154:155] op_sel_hi:[1,0]
	v_pk_mul_f32 v[100:101], v[100:101], v[154:155] op_sel_hi:[1,0]
	v_pk_mul_f32 v[96:97], v[96:97], v[154:155] op_sel_hi:[1,0]
	v_pk_mul_f32 v[98:99], v[98:99], v[154:155] op_sel_hi:[1,0]
	s_waitcnt vmcnt(5)
	v_mov_b32_e32 v160, v179
	v_mov_b32_e32 v161, v180
	v_mov_b32_e32 v179, v181
	v_pk_add_f32 v[160:161], v[160:161], v[178:179]
	s_waitcnt vmcnt(4)
	v_mov_b32_e32 v130, v183
	v_mov_b32_e32 v131, v184
	v_mov_b32_e32 v183, v185
	v_pk_add_f32 v[130:131], v[130:131], v[182:183]
	v_mov_b32_e32 v165, v160
	v_mov_b32_e32 v164, v130
	v_mov_b32_e32 v160, v131
	v_pk_add_f32 v[130:131], v[164:165], v[160:161]
	ds_bpermute_b32 v161, v162, v131
	ds_bpermute_b32 v160, v162, v130
	s_waitcnt lgkmcnt(0)
	v_pk_add_f32 v[130:131], v[130:131], v[160:161]
	ds_bpermute_b32 v161, v157, v131
	ds_bpermute_b32 v160, v157, v130
	s_waitcnt lgkmcnt(0)
	v_pk_add_f32 v[130:131], v[130:131], v[160:161]
	s_nop 0
	v_pk_fma_f32 v[130:131], v[130:131], s[38:39], v[158:159] op_sel_hi:[1,0,0]
	s_nop 0
	v_mul_f32_e32 v146, 0x4b800000, v131
	v_cmp_gt_f32_e64 s[42:43], s99, v131
	v_cmp_gt_f32_e32 vcc, s99, v130
	s_nop 0
	v_cndmask_b32_e64 v131, v131, v146, s[42:43]
	v_rsq_f32_e32 v131, v131
	s_nop 0
	v_mul_f32_e32 v146, 0x45800000, v131
	v_cndmask_b32_e64 v152, v131, v146, s[42:43]
	v_mul_f32_e32 v131, 0x4b800000, v130
	v_cndmask_b32_e32 v130, v130, v131, vcc
	v_rsq_f32_e32 v130, v130
	v_pk_mul_f32 v[92:93], v[92:93], v[152:153] op_sel_hi:[1,0]
	v_pk_mul_f32 v[88:89], v[88:89], v[152:153] op_sel_hi:[1,0]
	v_pk_mul_f32 v[90:91], v[90:91], v[152:153] op_sel_hi:[1,0]
	v_mul_f32_e32 v131, 0x45800000, v130
	v_cndmask_b32_e32 v150, v130, v131, vcc
	v_pk_mul_f32 v[84:85], v[84:85], v[152:153] op_sel_hi:[1,0]
	v_pk_mul_f32 v[80:81], v[80:81], v[152:153] op_sel_hi:[1,0]
	v_pk_mul_f32 v[82:83], v[82:83], v[152:153] op_sel_hi:[1,0]
	v_pk_mul_f32 v[76:77], v[76:77], v[150:151] op_sel_hi:[1,0]
	v_pk_mul_f32 v[72:73], v[72:73], v[150:151] op_sel_hi:[1,0]
	v_pk_mul_f32 v[74:75], v[74:75], v[150:151] op_sel_hi:[1,0]
	v_pk_mul_f32 v[68:69], v[68:69], v[150:151] op_sel_hi:[1,0]
	v_pk_mul_f32 v[64:65], v[64:65], v[150:151] op_sel_hi:[1,0]
	v_pk_mul_f32 v[66:67], v[66:67], v[150:151] op_sel_hi:[1,0]
	s_waitcnt vmcnt(3)
	v_mov_b32_e32 v130, v187
	v_mov_b32_e32 v131, v188
	v_mov_b32_e32 v187, v189
	v_pk_add_f32 v[130:131], v[130:131], v[186:187]
	s_waitcnt vmcnt(2)
; __device__ __forceinline__ u32x4 pack8(const f32x4& a, const f32x4& b) { u32x4 w; w.x = pk2(a[0], a[1]); w.y = pk2(a[2], a[3]); w.z = pk2(b[0], b[1]); w.w = pk2(b[2], b[3]); return w; }
; __device__ __forceinline__ float sigm(float x) { return __builtin_amdgcn_rcpf(1.0f + __builtin_amdgcn_exp2f(x * -1.4426950408889634f)); }
;     __device__ __forceinline__ void operator()(const f32x4 (&acc)[2][2][4][2], const Unit& u, int wr, int wc, int fr, int fq) const {
;     ...
;             for (int m = 0; m < 4; ++m) rx[ai][m] = row_rstd(ssp, row0 + ai * HALF + m * 16, fq);
; #pragma unroll
;         for (int ai = 0; ai < 2; ++ai)
; #pragma unroll
;             for (int m = 0; m < 4; ++m) { f32x4 o[2];
; #pragma unroll
;                 for (int n = 0; n < 2; ++n) { const f32x4 a = acc[ai][0][m][n] * rx[ai][m], b = acc[ai][1][m][n] * rx[ai][m];
; #pragma unroll
;                     for (int e = 0; e < 4; ++e) o[n][e] = a[e] * sigm(a[e]) * b[e]; }
;                 *(u32x4*)(H + (size_t)(lrow0 + ai * HALF + m * 16) * DFF + col0) = pack8(o[0], o[1]); asm volatile("" ::: "memory"); }
	v_mov_b32_e32 v160, v195
	v_mov_b32_e32 v161, v196
	v_mov_b32_e32 v195, v197
	v_pk_add_f32 v[160:161], v[160:161], v[194:195]
	v_mov_b32_e32 v165, v130
	v_mov_b32_e32 v164, v160
	v_mov_b32_e32 v130, v161
	v_pk_add_f32 v[130:131], v[164:165], v[130:131]
	ds_bpermute_b32 v161, v162, v131
	ds_bpermute_b32 v160, v162, v130
	s_waitcnt lgkmcnt(0)
	v_pk_add_f32 v[130:131], v[130:131], v[160:161]
	ds_bpermute_b32 v161, v157, v131
	ds_bpermute_b32 v160, v157, v130
	s_waitcnt lgkmcnt(0)
	v_pk_add_f32 v[130:131], v[130:131], v[160:161]
	s_nop 0
	v_pk_fma_f32 v[130:131], v[130:131], s[38:39], v[158:159] op_sel_hi:[1,0,0]
	s_nop 0
	v_mul_f32_e32 v146, 0x4b800000, v131
	v_cmp_gt_f32_e64 s[42:43], s99, v131
	v_cmp_gt_f32_e32 vcc, s99, v130
	s_nop 0
	v_cndmask_b32_e64 v131, v131, v146, s[42:43]
	v_rsq_f32_e32 v131, v131
	s_nop 0
	v_mul_f32_e32 v146, 0x45800000, v131
	v_cndmask_b32_e64 v148, v131, v146, s[42:43]
	v_mul_f32_e32 v131, 0x4b800000, v130
	v_cndmask_b32_e32 v130, v130, v131, vcc
	v_rsq_f32_e32 v130, v130
	v_pk_mul_f32 v[60:61], v[60:61], v[148:149] op_sel_hi:[1,0]
	v_pk_mul_f32 v[56:57], v[56:57], v[148:149] op_sel_hi:[1,0]
	v_pk_mul_f32 v[58:59], v[58:59], v[148:149] op_sel_hi:[1,0]
	v_mul_f32_e32 v131, 0x45800000, v130
	v_cndmask_b32_e32 v146, v130, v131, vcc
	v_pk_mul_f32 v[52:53], v[52:53], v[148:149] op_sel_hi:[1,0]
	v_pk_mul_f32 v[48:49], v[48:49], v[148:149] op_sel_hi:[1,0]
	v_pk_mul_f32 v[50:51], v[50:51], v[148:149] op_sel_hi:[1,0]
	v_pk_mul_f32 v[44:45], v[44:45], v[146:147] op_sel_hi:[1,0]
	v_pk_mul_f32 v[40:41], v[40:41], v[146:147] op_sel_hi:[1,0]
	v_pk_mul_f32 v[42:43], v[42:43], v[146:147] op_sel_hi:[1,0]
	v_pk_mul_f32 v[36:37], v[36:37], v[146:147] op_sel_hi:[1,0]
	v_pk_mul_f32 v[32:33], v[32:33], v[146:147] op_sel_hi:[1,0]
	v_pk_mul_f32 v[34:35], v[34:35], v[146:147] op_sel_hi:[1,0]
	s_waitcnt vmcnt(1)
	v_mov_b32_e32 v130, v199
	v_mov_b32_e32 v131, v200
	v_mov_b32_e32 v199, v201
	v_pk_add_f32 v[160:161], v[130:131], v[198:199]
	s_waitcnt vmcnt(0)
	v_mov_b32_e32 v164, v203
	v_mov_b32_e32 v165, v204
	v_mov_b32_e32 v203, v205
	v_pk_add_f32 v[128:129], v[164:165], v[202:203]
	v_mov_b32_e32 v131, v160
	v_mov_b32_e32 v130, v128
	v_mov_b32_e32 v160, v129
	v_pk_add_f32 v[128:129], v[130:131], v[160:161]
	ds_bpermute_b32 v131, v162, v129
	ds_bpermute_b32 v130, v162, v128
	s_waitcnt lgkmcnt(0)
	v_pk_add_f32 v[128:129], v[128:129], v[130:131]
	ds_bpermute_b32 v131, v157, v129
	ds_bpermute_b32 v130, v157, v128
	s_waitcnt lgkmcnt(0)
	v_pk_add_f32 v[128:129], v[128:129], v[130:131]
	s_nop 0
	v_pk_fma_f32 v[128:129], v[128:129], s[38:39], v[158:159] op_sel_hi:[1,0,0]
	v_lshl_or_b32 v158, s59, 7, v151
	v_mul_f32_e32 v130, 0x4b800000, v129
	v_cmp_gt_f32_e64 s[42:43], s99, v129
	v_cmp_gt_f32_e32 vcc, s99, v128
	v_ashrrev_i32_e32 v159, 31, v158
	v_cndmask_b32_e64 v129, v129, v130, s[42:43]
	v_rsq_f32_e32 v129, v129
	v_lshl_add_u64 v[158:159], v[158:159], 1, s[10:11]
	v_mul_f32_e32 v130, 0x45800000, v129
	v_cndmask_b32_e64 v130, v129, v130, s[42:43]
	v_mul_f32_e32 v129, 0x4b800000, v128
	v_cndmask_b32_e32 v128, v128, v129, vcc
	v_rsq_f32_e32 v128, v128
	v_pk_mul_f32 v[28:29], v[28:29], v[130:131] op_sel_hi:[1,0]
	v_pk_mul_f32 v[24:25], v[24:25], v[130:131] op_sel_hi:[1,0]
	v_pk_mul_f32 v[26:27], v[26:27], v[130:131] op_sel_hi:[1,0]
	v_mul_f32_e32 v129, 0x45800000, v128
	v_cndmask_b32_e32 v128, v128, v129, vcc
	v_mul_f32_e32 v129, 0xbfb8aa3b, v124
	v_exp_f32_e32 v129, v129
	v_pk_mul_f32 v[20:21], v[20:21], v[130:131] op_sel_hi:[1,0]
	v_pk_mul_f32 v[16:17], v[16:17], v[130:131] op_sel_hi:[1,0]
	v_pk_mul_f32 v[18:19], v[18:19], v[130:131] op_sel_hi:[1,0]
	v_add_f32_e32 v129, 1.0, v129
	v_rcp_f32_e32 v160, v129
	v_mul_f32_e32 v129, 0xbfb8aa3b, v125
	v_exp_f32_e32 v129, v129
	s_mov_b64 s[42:43], -1
	v_add_f32_e32 v129, 1.0, v129
	v_rcp_f32_e32 v161, v129
	v_pk_mul_f32 v[12:13], v[12:13], v[128:129] op_sel_hi:[1,0]
	v_pk_mul_f32 v[8:9], v[8:9], v[128:129] op_sel_hi:[1,0]
	v_pk_mul_f32 v[10:11], v[10:11], v[128:129] op_sel_hi:[1,0]
	v_pk_mul_f32 v[124:125], v[124:125], v[160:161]
	v_pk_mul_f32 v[4:5], v[4:5], v[128:129] op_sel_hi:[1,0]
	v_pk_mul_f32 v[120:121], v[120:121], v[124:125]
	v_pk_mul_f32 v[124:125], v[126:127], v[156:157] op_sel_hi:[1,0]
	v_pk_mul_f32 v[0:1], v[0:1], v[128:129] op_sel_hi:[1,0]
	v_mul_f32_e32 v126, 0xbfb8aa3b, v124
	v_mul_f32_e32 v127, 0xbfb8aa3b, v125
	v_exp_f32_e32 v126, v126
	v_exp_f32_e32 v127, v127
	v_pk_mul_f32 v[2:3], v[2:3], v[128:129] op_sel_hi:[1,0]
	v_add_f32_e32 v126, 1.0, v126
	v_add_f32_e32 v127, 1.0, v127
	v_rcp_f32_e32 v126, v126
	v_rcp_f32_e32 v127, v127
	s_nop 0
	v_pk_mul_f32 v[124:125], v[124:125], v[126:127]
	s_nop 0
	v_pk_mul_f32 v[122:123], v[122:123], v[124:125]
	v_mul_f32_e32 v124, 0xbfb8aa3b, v116
	v_mul_f32_e32 v125, 0xbfb8aa3b, v117
	v_exp_f32_e32 v124, v124
	v_exp_f32_e32 v125, v125
	v_add_f32_e32 v124, 1.0, v124
	v_add_f32_e32 v125, 1.0, v125
	v_rcp_f32_e32 v124, v124
	v_rcp_f32_e32 v125, v125
	s_nop 0
	v_pk_mul_f32 v[116:117], v[116:117], v[124:125]
	s_nop 0
	v_pk_mul_f32 v[112:113], v[112:113], v[116:117]
	v_pk_mul_f32 v[116:117], v[118:119], v[156:157] op_sel_hi:[1,0]
	s_nop 0
	v_mul_f32_e32 v118, 0xbfb8aa3b, v116
	v_mul_f32_e32 v119, 0xbfb8aa3b, v117
	v_exp_f32_e32 v118, v118
	v_exp_f32_e32 v119, v119
	v_add_f32_e32 v118, 1.0, v118
	v_add_f32_e32 v119, 1.0, v119
	v_rcp_f32_e32 v118, v118
	v_rcp_f32_e32 v119, v119
	s_nop 0
	v_pk_mul_f32 v[116:117], v[116:117], v[118:119]
	s_nop 0
	v_pk_mul_f32 v[118:119], v[114:115], v[116:117]
	v_cvt_pk_bf16_f32 v116, v112, v113
	v_mul_u32_u24_e32 v112, 0xb00, v155
	v_lshlrev_b32_e32 v192, 1, v112
	v_cvt_pk_bf16_f32 v114, v120, v121
	v_cvt_pk_bf16_f32 v115, v122, v123
; __device__ __forceinline__ u32x4 pack8(const f32x4& a, const f32x4& b) { u32x4 w; w.x = pk2(a[0], a[1]); w.y = pk2(a[2], a[3]); w.z = pk2(b[0], b[1]); w.w = pk2(b[2], b[3]); return w; }
; __device__ __forceinline__ float sigm(float x) { return __builtin_amdgcn_rcpf(1.0f + __builtin_amdgcn_exp2f(x * -1.4426950408889634f)); }
;     __device__ __forceinline__ void operator()(const f32x4 (&acc)[2][2][4][2], const Unit& u, int wr, int wc, int fr, int fq) const {
;     ...
;         for (int ai = 0; ai < 2; ++ai)
; #pragma unroll
;             for (int m = 0; m < 4; ++m) { f32x4 o[2];
; #pragma unroll
;                 for (int n = 0; n < 2; ++n) { const f32x4 a = acc[ai][0][m][n] * rx[ai][m], b = acc[ai][1][m][n] * rx[ai][m];
; #pragma unroll
;                     for (int e = 0; e < 4; ++e) o[n][e] = a[e] * sigm(a[e]) * b[e]; }
;                 *(u32x4*)(H + (size_t)(lrow0 + ai * HALF + m * 16) * DFF + col0) = pack8(o[0], o[1]); asm volatile("" ::: "memory"); }
	v_cvt_pk_bf16_f32 v117, v118, v119
	v_lshl_add_u64 v[112:113], v[158:159], 0, v[192:193]
	global_store_dwordx4 v[112:113], v[114:117], off
	s_nop 1
	v_mul_f32_e32 v114, 0xbfb8aa3b, v108
	v_mul_f32_e32 v115, 0xbfb8aa3b, v109
	v_exp_f32_e32 v114, v114
	v_exp_f32_e32 v115, v115
	v_add_f32_e32 v114, 1.0, v114
	v_add_f32_e32 v115, 1.0, v115
	v_rcp_f32_e32 v114, v114
	v_rcp_f32_e32 v115, v115
	s_nop 0
	v_pk_mul_f32 v[108:109], v[108:109], v[114:115]
	s_nop 0
	v_pk_mul_f32 v[104:105], v[104:105], v[108:109]
	v_pk_mul_f32 v[108:109], v[110:111], v[154:155] op_sel_hi:[1,0]
	s_nop 0
	v_mul_f32_e32 v110, 0xbfb8aa3b, v108
	v_mul_f32_e32 v111, 0xbfb8aa3b, v109
	v_exp_f32_e32 v110, v110
	v_exp_f32_e32 v111, v111
	v_add_f32_e32 v110, 1.0, v110
	v_add_f32_e32 v111, 1.0, v111
	v_rcp_f32_e32 v110, v110
	v_rcp_f32_e32 v111, v111
	s_nop 0
	v_pk_mul_f32 v[108:109], v[108:109], v[110:111]
	s_nop 0
	v_pk_mul_f32 v[106:107], v[106:107], v[108:109]
	v_mul_f32_e32 v108, 0xbfb8aa3b, v100
	v_mul_f32_e32 v109, 0xbfb8aa3b, v101
	v_exp_f32_e32 v108, v108
	v_exp_f32_e32 v109, v109
	v_add_f32_e32 v108, 1.0, v108
	v_add_f32_e32 v109, 1.0, v109
	v_rcp_f32_e32 v108, v108
	v_rcp_f32_e32 v109, v109
	s_nop 0
	v_pk_mul_f32 v[100:101], v[100:101], v[108:109]
	s_nop 0
	v_pk_mul_f32 v[100:101], v[96:97], v[100:101]
	v_pk_mul_f32 v[96:97], v[102:103], v[154:155] op_sel_hi:[1,0]
	s_nop 0
	v_mul_f32_e32 v102, 0xbfb8aa3b, v96
	v_mul_f32_e32 v103, 0xbfb8aa3b, v97
	v_exp_f32_e32 v102, v102
	v_exp_f32_e32 v103, v103
	v_add_f32_e32 v102, 1.0, v102
	v_add_f32_e32 v103, 1.0, v103
	v_rcp_f32_e32 v102, v102
	v_rcp_f32_e32 v103, v103
	s_nop 0
	v_pk_mul_f32 v[96:97], v[96:97], v[102:103]
	s_nop 0
	v_pk_mul_f32 v[102:103], v[98:99], v[96:97]
	v_cvt_pk_bf16_f32 v98, v100, v101
	v_add_co_u32_e32 v100, vcc, s69, v112
	v_cvt_pk_bf16_f32 v96, v104, v105
	v_cvt_pk_bf16_f32 v97, v106, v107
	v_cvt_pk_bf16_f32 v99, v102, v103
	v_addc_co_u32_e32 v101, vcc, 0, v113, vcc
	global_store_dwordx4 v[100:101], v[96:99], off
	s_nop 1
	v_mul_f32_e32 v96, 0xbfb8aa3b, v92
	v_mul_f32_e32 v97, 0xbfb8aa3b, v93
	v_exp_f32_e32 v96, v96
	v_exp_f32_e32 v97, v97
	v_add_f32_e32 v96, 1.0, v96
	v_add_f32_e32 v97, 1.0, v97
	v_rcp_f32_e32 v96, v96
	v_rcp_f32_e32 v97, v97
	s_nop 0
	v_pk_mul_f32 v[92:93], v[92:93], v[96:97]
	s_nop 0
	v_pk_mul_f32 v[88:89], v[88:89], v[92:93]
	v_pk_mul_f32 v[92:93], v[94:95], v[152:153] op_sel_hi:[1,0]
	s_nop 0
	v_mul_f32_e32 v94, 0xbfb8aa3b, v92
	v_mul_f32_e32 v95, 0xbfb8aa3b, v93
	v_exp_f32_e32 v94, v94
	v_exp_f32_e32 v95, v95
	v_add_f32_e32 v94, 1.0, v94
	v_add_f32_e32 v95, 1.0, v95
	v_rcp_f32_e32 v94, v94
	v_rcp_f32_e32 v95, v95
	s_nop 0
	v_pk_mul_f32 v[92:93], v[92:93], v[94:95]
	s_nop 0
	v_pk_mul_f32 v[90:91], v[90:91], v[92:93]
	v_mul_f32_e32 v92, 0xbfb8aa3b, v84
	v_mul_f32_e32 v93, 0xbfb8aa3b, v85
	v_exp_f32_e32 v92, v92
	v_exp_f32_e32 v93, v93
	v_add_f32_e32 v92, 1.0, v92
	v_add_f32_e32 v93, 1.0, v93
	v_rcp_f32_e32 v92, v92
	v_rcp_f32_e32 v93, v93
	s_nop 0
	v_pk_mul_f32 v[84:85], v[84:85], v[92:93]
	s_nop 0
	v_pk_mul_f32 v[84:85], v[80:81], v[84:85]
	v_pk_mul_f32 v[80:81], v[86:87], v[152:153] op_sel_hi:[1,0]
	s_nop 0
	v_mul_f32_e32 v86, 0xbfb8aa3b, v80
	v_mul_f32_e32 v87, 0xbfb8aa3b, v81
	v_exp_f32_e32 v86, v86
	v_exp_f32_e32 v87, v87
	v_add_f32_e32 v86, 1.0, v86
	v_add_f32_e32 v87, 1.0, v87
	v_rcp_f32_e32 v86, v86
	v_rcp_f32_e32 v87, v87
	s_nop 0
	v_pk_mul_f32 v[80:81], v[80:81], v[86:87]
	s_nop 0
	v_pk_mul_f32 v[86:87], v[82:83], v[80:81]
	v_cvt_pk_bf16_f32 v82, v84, v85
	v_add_co_u32_e32 v84, vcc, s73, v112
	v_cvt_pk_bf16_f32 v80, v88, v89
	v_cvt_pk_bf16_f32 v81, v90, v91
	v_cvt_pk_bf16_f32 v83, v86, v87
	v_addc_co_u32_e32 v85, vcc, 0, v113, vcc
	global_store_dwordx4 v[84:85], v[80:83], off
	s_nop 1
	v_mul_f32_e32 v80, 0xbfb8aa3b, v76
	v_mul_f32_e32 v81, 0xbfb8aa3b, v77
	v_exp_f32_e32 v80, v80
	v_exp_f32_e32 v81, v81
	v_add_f32_e32 v80, 1.0, v80
	v_add_f32_e32 v81, 1.0, v81
	v_rcp_f32_e32 v80, v80
	v_rcp_f32_e32 v81, v81
	s_nop 0
	v_pk_mul_f32 v[76:77], v[76:77], v[80:81]
	s_nop 0
	v_pk_mul_f32 v[72:73], v[72:73], v[76:77]
	v_pk_mul_f32 v[76:77], v[78:79], v[150:151] op_sel_hi:[1,0]
	s_nop 0
	v_mul_f32_e32 v78, 0xbfb8aa3b, v76
	v_mul_f32_e32 v79, 0xbfb8aa3b, v77
	v_exp_f32_e32 v78, v78
	v_exp_f32_e32 v79, v79
	v_add_f32_e32 v78, 1.0, v78
	v_add_f32_e32 v79, 1.0, v79
	v_rcp_f32_e32 v78, v78
	v_rcp_f32_e32 v79, v79
	s_nop 0
	v_pk_mul_f32 v[76:77], v[76:77], v[78:79]
	s_nop 0
	v_pk_mul_f32 v[74:75], v[74:75], v[76:77]
	v_mul_f32_e32 v76, 0xbfb8aa3b, v68
	v_mul_f32_e32 v77, 0xbfb8aa3b, v69
	v_exp_f32_e32 v76, v76
	v_exp_f32_e32 v77, v77
	v_add_f32_e32 v76, 1.0, v76
	v_add_f32_e32 v77, 1.0, v77
	v_rcp_f32_e32 v76, v76
	v_rcp_f32_e32 v77, v77
	s_nop 0
	v_pk_mul_f32 v[68:69], v[68:69], v[76:77]
	s_nop 0
	v_pk_mul_f32 v[68:69], v[64:65], v[68:69]
	v_pk_mul_f32 v[64:65], v[70:71], v[150:151] op_sel_hi:[1,0]
	s_nop 0
	v_mul_f32_e32 v70, 0xbfb8aa3b, v64
	v_mul_f32_e32 v71, 0xbfb8aa3b, v65
	v_exp_f32_e32 v70, v70
	v_exp_f32_e32 v71, v71
	v_add_f32_e32 v70, 1.0, v70
	v_add_f32_e32 v71, 1.0, v71
	v_rcp_f32_e32 v70, v70
	v_rcp_f32_e32 v71, v71
	s_nop 0
	v_pk_mul_f32 v[64:65], v[64:65], v[70:71]
	s_nop 0
	v_pk_mul_f32 v[70:71], v[66:67], v[64:65]
	v_cvt_pk_bf16_f32 v66, v68, v69
	v_add_co_u32_e32 v68, vcc, s74, v112
	v_cvt_pk_bf16_f32 v64, v72, v73
	v_cvt_pk_bf16_f32 v65, v74, v75
	v_cvt_pk_bf16_f32 v67, v70, v71
	v_addc_co_u32_e32 v69, vcc, 0, v113, vcc
	global_store_dwordx4 v[68:69], v[64:67], off
	s_nop 1
	v_mul_f32_e32 v64, 0xbfb8aa3b, v60
	v_mul_f32_e32 v65, 0xbfb8aa3b, v61
	v_exp_f32_e32 v64, v64
	v_exp_f32_e32 v65, v65
	v_add_f32_e32 v64, 1.0, v64
	v_add_f32_e32 v65, 1.0, v65
	v_rcp_f32_e32 v64, v64
; __device__ __forceinline__ u32x4 pack8(const f32x4& a, const f32x4& b) { u32x4 w; w.x = pk2(a[0], a[1]); w.y = pk2(a[2], a[3]); w.z = pk2(b[0], b[1]); w.w = pk2(b[2], b[3]); return w; }
; __device__ __forceinline__ float sigm(float x) { return __builtin_amdgcn_rcpf(1.0f + __builtin_amdgcn_exp2f(x * -1.4426950408889634f)); }
;     __device__ __forceinline__ void operator()(const f32x4 (&acc)[2][2][4][2], const Unit& u, int wr, int wc, int fr, int fq) const {
;     ...
;         for (int ai = 0; ai < 2; ++ai)
; #pragma unroll
;             for (int m = 0; m < 4; ++m) { f32x4 o[2];
; #pragma unroll
;                 for (int n = 0; n < 2; ++n) { const f32x4 a = acc[ai][0][m][n] * rx[ai][m], b = acc[ai][1][m][n] * rx[ai][m];
; #pragma unroll
;                     for (int e = 0; e < 4; ++e) o[n][e] = a[e] * sigm(a[e]) * b[e]; }
;                 *(u32x4*)(H + (size_t)(lrow0 + ai * HALF + m * 16) * DFF + col0) = pack8(o[0], o[1]); asm volatile("" ::: "memory"); }
	v_rcp_f32_e32 v65, v65
	s_nop 0
	v_pk_mul_f32 v[60:61], v[60:61], v[64:65]
	s_nop 0
	v_pk_mul_f32 v[56:57], v[56:57], v[60:61]
	v_pk_mul_f32 v[60:61], v[62:63], v[148:149] op_sel_hi:[1,0]
	s_nop 0
	v_mul_f32_e32 v62, 0xbfb8aa3b, v60
	v_mul_f32_e32 v63, 0xbfb8aa3b, v61
	v_exp_f32_e32 v62, v62
	v_exp_f32_e32 v63, v63
	v_add_f32_e32 v62, 1.0, v62
	v_add_f32_e32 v63, 1.0, v63
	v_rcp_f32_e32 v62, v62
	v_rcp_f32_e32 v63, v63
	s_nop 0
	v_pk_mul_f32 v[60:61], v[60:61], v[62:63]
	s_nop 0
	v_pk_mul_f32 v[58:59], v[58:59], v[60:61]
	v_mul_f32_e32 v60, 0xbfb8aa3b, v52
	v_mul_f32_e32 v61, 0xbfb8aa3b, v53
	v_exp_f32_e32 v60, v60
	v_exp_f32_e32 v61, v61
	v_add_f32_e32 v60, 1.0, v60
	v_add_f32_e32 v61, 1.0, v61
	v_rcp_f32_e32 v60, v60
	v_rcp_f32_e32 v61, v61
	s_nop 0
	v_pk_mul_f32 v[52:53], v[52:53], v[60:61]
	s_nop 0
	v_pk_mul_f32 v[52:53], v[48:49], v[52:53]
	v_pk_mul_f32 v[48:49], v[54:55], v[148:149] op_sel_hi:[1,0]
	s_nop 0
	v_mul_f32_e32 v54, 0xbfb8aa3b, v48
	v_mul_f32_e32 v55, 0xbfb8aa3b, v49
	v_exp_f32_e32 v54, v54
	v_exp_f32_e32 v55, v55
	v_add_f32_e32 v54, 1.0, v54
	v_add_f32_e32 v55, 1.0, v55
	v_rcp_f32_e32 v54, v54
	v_rcp_f32_e32 v55, v55
	s_nop 0
	v_pk_mul_f32 v[48:49], v[48:49], v[54:55]
	s_nop 0
	v_pk_mul_f32 v[54:55], v[50:51], v[48:49]
	v_cvt_pk_bf16_f32 v50, v52, v53
	v_add_co_u32_e32 v52, vcc, s75, v112
	v_cvt_pk_bf16_f32 v48, v56, v57
	v_cvt_pk_bf16_f32 v49, v58, v59
	v_cvt_pk_bf16_f32 v51, v54, v55
	v_addc_co_u32_e32 v53, vcc, 0, v113, vcc
	global_store_dwordx4 v[52:53], v[48:51], off
	s_nop 1
	v_mul_f32_e32 v48, 0xbfb8aa3b, v44
	v_mul_f32_e32 v49, 0xbfb8aa3b, v45
	v_exp_f32_e32 v48, v48
	v_exp_f32_e32 v49, v49
	v_add_f32_e32 v48, 1.0, v48
	v_add_f32_e32 v49, 1.0, v49
	v_rcp_f32_e32 v48, v48
	v_rcp_f32_e32 v49, v49
	s_nop 0
	v_pk_mul_f32 v[44:45], v[44:45], v[48:49]
	s_nop 0
	v_pk_mul_f32 v[40:41], v[40:41], v[44:45]
	v_pk_mul_f32 v[44:45], v[46:47], v[146:147] op_sel_hi:[1,0]
	s_nop 0
	v_mul_f32_e32 v46, 0xbfb8aa3b, v44
	v_mul_f32_e32 v47, 0xbfb8aa3b, v45
	v_exp_f32_e32 v46, v46
	v_exp_f32_e32 v47, v47
	v_add_f32_e32 v46, 1.0, v46
	v_add_f32_e32 v47, 1.0, v47
	v_rcp_f32_e32 v46, v46
	v_rcp_f32_e32 v47, v47
	s_nop 0
	v_pk_mul_f32 v[44:45], v[44:45], v[46:47]
	s_nop 0
	v_pk_mul_f32 v[42:43], v[42:43], v[44:45]
	v_mul_f32_e32 v44, 0xbfb8aa3b, v36
	v_mul_f32_e32 v45, 0xbfb8aa3b, v37
	v_exp_f32_e32 v44, v44
	v_exp_f32_e32 v45, v45
	v_add_f32_e32 v44, 1.0, v44
	v_add_f32_e32 v45, 1.0, v45
	v_rcp_f32_e32 v44, v44
	v_rcp_f32_e32 v45, v45
	s_nop 0
	v_pk_mul_f32 v[36:37], v[36:37], v[44:45]
	s_nop 0
	v_pk_mul_f32 v[36:37], v[32:33], v[36:37]
	v_pk_mul_f32 v[32:33], v[38:39], v[146:147] op_sel_hi:[1,0]
	s_nop 0
	v_mul_f32_e32 v38, 0xbfb8aa3b, v32
	v_mul_f32_e32 v39, 0xbfb8aa3b, v33
	v_exp_f32_e32 v38, v38
	v_exp_f32_e32 v39, v39
	v_add_f32_e32 v38, 1.0, v38
	v_add_f32_e32 v39, 1.0, v39
	v_rcp_f32_e32 v38, v38
	v_rcp_f32_e32 v39, v39
	s_nop 0
	v_pk_mul_f32 v[32:33], v[32:33], v[38:39]
	s_nop 0
	v_pk_mul_f32 v[38:39], v[34:35], v[32:33]
	v_cvt_pk_bf16_f32 v34, v36, v37
	v_add_co_u32_e32 v36, vcc, s76, v112
	v_cvt_pk_bf16_f32 v32, v40, v41
	v_cvt_pk_bf16_f32 v33, v42, v43
	v_cvt_pk_bf16_f32 v35, v38, v39
	v_addc_co_u32_e32 v37, vcc, 0, v113, vcc
	global_store_dwordx4 v[36:37], v[32:35], off
	s_nop 1
	v_mul_f32_e32 v32, 0xbfb8aa3b, v28
	v_mul_f32_e32 v33, 0xbfb8aa3b, v29
	v_exp_f32_e32 v32, v32
	v_exp_f32_e32 v33, v33
	v_add_f32_e32 v32, 1.0, v32
	v_add_f32_e32 v33, 1.0, v33
	v_rcp_f32_e32 v32, v32
	v_rcp_f32_e32 v33, v33
	s_nop 0
	v_pk_mul_f32 v[28:29], v[28:29], v[32:33]
	s_nop 0
	v_pk_mul_f32 v[24:25], v[24:25], v[28:29]
	v_pk_mul_f32 v[28:29], v[30:31], v[130:131] op_sel_hi:[1,0]
	s_nop 0
	v_mul_f32_e32 v30, 0xbfb8aa3b, v28
	v_mul_f32_e32 v31, 0xbfb8aa3b, v29
	v_exp_f32_e32 v30, v30
	v_exp_f32_e32 v31, v31
	v_add_f32_e32 v30, 1.0, v30
	v_add_f32_e32 v31, 1.0, v31
	v_rcp_f32_e32 v30, v30
	v_rcp_f32_e32 v31, v31
	s_nop 0
	v_pk_mul_f32 v[28:29], v[28:29], v[30:31]
	s_nop 0
	v_pk_mul_f32 v[26:27], v[26:27], v[28:29]
	v_mul_f32_e32 v28, 0xbfb8aa3b, v20
	v_mul_f32_e32 v29, 0xbfb8aa3b, v21
	v_exp_f32_e32 v28, v28
	v_exp_f32_e32 v29, v29
	v_add_f32_e32 v28, 1.0, v28
	v_add_f32_e32 v29, 1.0, v29
	v_rcp_f32_e32 v28, v28
	v_rcp_f32_e32 v29, v29
	s_nop 0
	v_pk_mul_f32 v[20:21], v[20:21], v[28:29]
	s_nop 0
	v_pk_mul_f32 v[20:21], v[16:17], v[20:21]
	v_pk_mul_f32 v[16:17], v[22:23], v[130:131] op_sel_hi:[1,0]
	s_nop 0
	v_mul_f32_e32 v22, 0xbfb8aa3b, v16
	v_mul_f32_e32 v23, 0xbfb8aa3b, v17
	v_exp_f32_e32 v22, v22
	v_exp_f32_e32 v23, v23
	v_add_f32_e32 v22, 1.0, v22
	v_add_f32_e32 v23, 1.0, v23
	v_rcp_f32_e32 v22, v22
	v_rcp_f32_e32 v23, v23
	s_nop 0
	v_pk_mul_f32 v[16:17], v[16:17], v[22:23]
	s_nop 0
	v_pk_mul_f32 v[22:23], v[18:19], v[16:17]
	v_cvt_pk_bf16_f32 v18, v20, v21
	v_add_co_u32_e32 v20, vcc, s77, v112
	v_cvt_pk_bf16_f32 v16, v24, v25
	v_cvt_pk_bf16_f32 v17, v26, v27
	v_cvt_pk_bf16_f32 v19, v22, v23
	v_addc_co_u32_e32 v21, vcc, 0, v113, vcc
	global_store_dwordx4 v[20:21], v[16:19], off
	s_nop 1
	v_mul_f32_e32 v16, 0xbfb8aa3b, v12
	v_mul_f32_e32 v17, 0xbfb8aa3b, v13
	v_exp_f32_e32 v16, v16
	v_exp_f32_e32 v17, v17
	v_add_f32_e32 v16, 1.0, v16
	v_add_f32_e32 v17, 1.0, v17
	v_rcp_f32_e32 v16, v16
	v_rcp_f32_e32 v17, v17
	s_nop 0
	v_pk_mul_f32 v[12:13], v[12:13], v[16:17]
	s_nop 0
	v_pk_mul_f32 v[8:9], v[8:9], v[12:13]
	v_pk_mul_f32 v[12:13], v[14:15], v[128:129] op_sel_hi:[1,0]
	s_nop 0
	v_mul_f32_e32 v14, 0xbfb8aa3b, v12
	v_mul_f32_e32 v15, 0xbfb8aa3b, v13
	v_exp_f32_e32 v14, v14
	v_exp_f32_e32 v15, v15
	v_add_f32_e32 v14, 1.0, v14
	v_add_f32_e32 v15, 1.0, v15
	v_rcp_f32_e32 v14, v14
	v_rcp_f32_e32 v15, v15
	s_nop 0
	v_pk_mul_f32 v[12:13], v[12:13], v[14:15]
	s_nop 0
	v_pk_mul_f32 v[10:11], v[10:11], v[12:13]
	v_mul_f32_e32 v12, 0xbfb8aa3b, v4
	v_mul_f32_e32 v13, 0xbfb8aa3b, v5
	v_exp_f32_e32 v12, v12
	v_exp_f32_e32 v13, v13
	v_add_f32_e32 v12, 1.0, v12
	v_add_f32_e32 v13, 1.0, v13
	v_rcp_f32_e32 v12, v12
	v_rcp_f32_e32 v13, v13
	s_nop 0
	v_pk_mul_f32 v[4:5], v[4:5], v[12:13]
	s_nop 0
	v_pk_mul_f32 v[4:5], v[0:1], v[4:5]
	v_pk_mul_f32 v[0:1], v[6:7], v[128:129] op_sel_hi:[1,0]
	s_nop 0
	v_mul_f32_e32 v6, 0xbfb8aa3b, v0
	v_mul_f32_e32 v7, 0xbfb8aa3b, v1
	v_exp_f32_e32 v6, v6
	v_exp_f32_e32 v7, v7
	v_add_f32_e32 v6, 1.0, v6
	v_add_f32_e32 v7, 1.0, v7
	v_rcp_f32_e32 v6, v6
	v_rcp_f32_e32 v7, v7
	s_nop 0
	v_pk_mul_f32 v[0:1], v[0:1], v[6:7]
	s_nop 0
	v_pk_mul_f32 v[6:7], v[2:3], v[0:1]
	v_cvt_pk_bf16_f32 v2, v4, v5
	v_add_co_u32_e32 v4, vcc, 0xf2000, v112
	v_cvt_pk_bf16_f32 v0, v8, v9
	v_cvt_pk_bf16_f32 v1, v10, v11
	v_cvt_pk_bf16_f32 v3, v6, v7
	v_addc_co_u32_e32 v5, vcc, 0, v113, vcc
	global_store_dwordx4 v[4:5], v[0:3], off
	s_andn2_b64 vcc, exec, s[40:41]
	s_cbranch_vccnz .LBB0_573
	s_andn2_b64 vcc, exec, s[22:23]
	s_cbranch_vccnz .LBB0_572
	s_barrier
	s_branch .LBB0_572
